# hand-written skinny jobs (P3/P4/P7): coalesced loads + lane transpose via ds_bpermute, 4-step prefetch ring, bank-swizzled LDS reduction, fused epilogues
# speedup vs baseline: 1.0744x; 1.0310x over previous
.LBB0_1622:
	v_readlane_b32 s4, v252, 56
	v_readlane_b32 s5, v252, 57
	s_mov_b64 s[6:7], s[0:1]
	s_mov_b64 s[14:15], s[0:1]
	v_cndmask_b32_e64 v0, 0, 1, s[4:5]
	v_cmp_ne_u32_e64 s[16:17], 1, v0
	s_mov_b64 s[8:9], s[0:1]
	s_mov_b64 s[10:11], s[0:1]
	v_writelane_b32 v255, s16, 19
	s_mov_b64 s[12:13], s[0:1]
	s_andn2_b64 vcc, exec, s[4:5]
	v_writelane_b32 v255, s17, 20
	s_cbranch_vccnz .LBB0_1626
	s_load_dwordx2 s[4:5], s[0:1], 0xb0
	v_readlane_b32 s6, v253, 49
	v_readfirstlane_b32 s9, v219
	v_and_b32_e32 v196, 63, v219
	v_lshrrev_b32_e32 v218, 3, v219
	v_and_b32_e32 v228, 7, v219
	s_lshr_b32 s6, s6, 9
	s_lshr_b32 s9, s9, 6
	s_lshr_b32 s7, s6, 5
	s_and_b32 s8, s6, 31
	s_lshl_b32 s8, s8, 6
	v_and_b32_e32 v197, 15, v196
	v_lshrrev_b32_e32 v198, 4, v196
	v_lshrrev_b32_e32 v199, 2, v196
	v_and_b32_e32 v200, 3, v196
	v_lshlrev_b32_e32 v6, 12, v199
	v_lshl_add_u32 v6, v200, 4, v6
	v_add_u32_e32 v7, 0x10000, v6
	v_add_u32_e32 v8, 0x20000, v6
	v_add_u32_e32 v56, 0x30000, v6
	v_lshlrev_b32_e32 v0, 2, v198
	v_lshl_add_u32 v0, v197, 4, v0
	v_and_b32_e32 v201, 3, v197
	v_xor_b32_e32 v201, v201, v198
	v_lshrrev_b32_e32 v202, 2, v197
	v_lshlrev_b32_e32 v203, 8, v197
	s_lshl_b32 s50, s9, 14
	v_add_u32_e32 v203, s50, v203
	v_xor_b32_e32 v57, 0, v202
	v_lshl_add_u32 v57, v57, 2, v201
	v_lshl_add_u32 v57, v57, 4, v203
	v_xor_b32_e32 v1, 1, v202
	v_lshl_add_u32 v1, v1, 2, v201
	v_lshl_add_u32 v1, v1, 4, v203
	v_xor_b32_e32 v234, 2, v202
	v_lshl_add_u32 v234, v234, 2, v201
	v_lshl_add_u32 v234, v234, 4, v203
	v_xor_b32_e32 v235, 3, v202
	v_lshl_add_u32 v235, v235, 2, v201
	v_lshl_add_u32 v235, v235, 4, v203
	v_and_b32_e32 v196, 15, v218
	v_lshlrev_b32_e32 v197, 1, v228
	v_xor_b32_e32 v196, v196, v197
	v_lshlrev_b32_e32 v59, 8, v218
	v_lshl_add_u32 v59, v196, 4, v59
	v_xor_b32_e32 v248, 16, v59
	v_add_u32_e32 v98, 0x10000, v59
	v_add_u32_e32 v249, 0x10000, v248
	v_lshlrev_b32_e32 v99, 12, v218
	v_lshl_add_u32 v99, v228, 4, v99
	s_lshl_b32 s60, s7, 6
	s_add_u32 s60, s60, 0x2000
	s_lshl_b32 s50, s60, 12
	s_lshl_b32 s51, s9, 8
	s_add_u32 s50, s50, s51
	s_lshl_b32 s61, s8, 12
	s_add_u32 s61, s61, s51
	s_lshl_b32 s62, s90, 23
	s_lshl_b32 s63, s60, 11
	s_add_u32 s63, s63, s8
	s_waitcnt lgkmcnt(0)
	s_add_u32 s10, s4, 0x18f00000
	s_addc_u32 s11, s5, 0
	s_add_u32 s10, s10, s50
	s_addc_u32 s11, s11, 0
	s_add_u32 s24, s4, 0x5400000
	s_addc_u32 s25, s5, 0
	s_add_u32 s24, s24, s62
	s_addc_u32 s25, s25, 0
	s_add_u32 s24, s24, s61
	s_addc_u32 s25, s25, 0
	s_lshl_b32 s64, s63, 1
	s_add_u32 s42, s4, 0x1b100000
	s_addc_u32 s43, s5, 0
	s_add_u32 s42, s42, s64
	s_addc_u32 s43, s43, 0
	s_add_u32 s44, s4, 0x1d300000
	s_addc_u32 s45, s5, 0
	s_add_u32 s44, s44, s63
	s_addc_u32 s45, s45, 0
	s_add_u32 s46, s4, 0x23900000
	s_addc_u32 s47, s5, 0
	s_add_u32 s46, s46, s64
	s_addc_u32 s47, s47, 0
	s_add_u32 s36, s10, 0x800
	s_addc_u32 s37, s11, 0
	s_add_u32 s66, s24, 0x800
	s_addc_u32 s67, s25, 0
	v_lshrrev_b32_e32 v230, 1, v99
	global_load_dwordx4 v[220:223], v99, s[42:43]
	global_load_dwordx2 v[238:239], v230, s[44:45]
	global_load_dwordx4 v[164:167], v6, s[10:11] offset:0
	global_load_dwordx4 v[168:171], v7, s[10:11] offset:0
	global_load_dwordx4 v[172:175], v8, s[10:11] offset:0
	global_load_dwordx4 v[176:179], v56, s[10:11] offset:0
	global_load_dwordx4 v[180:183], v6, s[24:25] offset:0
	global_load_dwordx4 v[184:187], v7, s[24:25] offset:0
	global_load_dwordx4 v[188:191], v8, s[24:25] offset:0
	global_load_dwordx4 v[192:195], v56, s[24:25] offset:0
	global_load_dwordx4 v[12:15], v6, s[10:11] offset:64
	global_load_dwordx4 v[16:19], v7, s[10:11] offset:64
	global_load_dwordx4 v[20:23], v8, s[10:11] offset:64
	global_load_dwordx4 v[24:27], v56, s[10:11] offset:64
	global_load_dwordx4 v[28:31], v6, s[24:25] offset:64
	global_load_dwordx4 v[32:35], v7, s[24:25] offset:64
	global_load_dwordx4 v[36:39], v8, s[24:25] offset:64
	global_load_dwordx4 v[40:43], v56, s[24:25] offset:64
	global_load_dwordx4 v[60:63], v6, s[10:11] offset:128
	global_load_dwordx4 v[64:67], v7, s[10:11] offset:128
	global_load_dwordx4 v[68:71], v8, s[10:11] offset:128
	global_load_dwordx4 v[72:75], v56, s[10:11] offset:128
	global_load_dwordx4 v[76:79], v6, s[24:25] offset:128
	global_load_dwordx4 v[80:83], v7, s[24:25] offset:128
	global_load_dwordx4 v[84:87], v8, s[24:25] offset:128
	global_load_dwordx4 v[88:91], v56, s[24:25] offset:128
	global_load_dwordx4 v[196:199], v6, s[10:11] offset:192
	global_load_dwordx4 v[200:203], v7, s[10:11] offset:192
	global_load_dwordx4 v[204:207], v8, s[10:11] offset:192
	global_load_dwordx4 v[208:211], v56, s[10:11] offset:192
	global_load_dwordx4 v[212:215], v6, s[24:25] offset:192
	global_load_dwordx4 v[44:47], v7, s[24:25] offset:192
	global_load_dwordx4 v[48:51], v8, s[24:25] offset:192
	global_load_dwordx4 v[52:55], v56, s[24:25] offset:192
	s_waitcnt vmcnt(24)
	ds_bpermute_b32 v164, v0, v164
	ds_bpermute_b32 v165, v0, v165
	ds_bpermute_b32 v166, v0, v166
	ds_bpermute_b32 v167, v0, v167
	ds_bpermute_b32 v168, v0, v168
	ds_bpermute_b32 v169, v0, v169
	ds_bpermute_b32 v170, v0, v170
	ds_bpermute_b32 v171, v0, v171
	ds_bpermute_b32 v172, v0, v172
	ds_bpermute_b32 v173, v0, v173
	ds_bpermute_b32 v174, v0, v174
	ds_bpermute_b32 v175, v0, v175
	ds_bpermute_b32 v176, v0, v176
	ds_bpermute_b32 v177, v0, v177
	ds_bpermute_b32 v178, v0, v178
	ds_bpermute_b32 v179, v0, v179
	ds_bpermute_b32 v180, v0, v180
	ds_bpermute_b32 v181, v0, v181
	ds_bpermute_b32 v182, v0, v182
	ds_bpermute_b32 v183, v0, v183
	ds_bpermute_b32 v184, v0, v184
	ds_bpermute_b32 v185, v0, v185
	ds_bpermute_b32 v186, v0, v186
	ds_bpermute_b32 v187, v0, v187
	ds_bpermute_b32 v188, v0, v188
	ds_bpermute_b32 v189, v0, v189
	ds_bpermute_b32 v190, v0, v190
	ds_bpermute_b32 v191, v0, v191
	ds_bpermute_b32 v192, v0, v192
	ds_bpermute_b32 v193, v0, v193
	ds_bpermute_b32 v194, v0, v194
	ds_bpermute_b32 v195, v0, v195
	s_waitcnt lgkmcnt(0)
	v_mfma_f32_16x16x32_bf16 v[100:103], v[180:183], v[164:167], 0
	v_mfma_f32_16x16x32_bf16 v[104:107], v[184:187], v[164:167], 0
	v_mfma_f32_16x16x32_bf16 v[108:111], v[188:191], v[164:167], 0
	v_mfma_f32_16x16x32_bf16 v[112:115], v[192:195], v[164:167], 0
	v_mfma_f32_16x16x32_bf16 v[116:119], v[180:183], v[168:171], 0
	v_mfma_f32_16x16x32_bf16 v[120:123], v[184:187], v[168:171], 0
	v_mfma_f32_16x16x32_bf16 v[124:127], v[188:191], v[168:171], 0
	v_mfma_f32_16x16x32_bf16 v[128:131], v[192:195], v[168:171], 0
	v_mfma_f32_16x16x32_bf16 v[132:135], v[180:183], v[172:175], 0
	v_mfma_f32_16x16x32_bf16 v[136:139], v[184:187], v[172:175], 0
	v_mfma_f32_16x16x32_bf16 v[140:143], v[188:191], v[172:175], 0
	v_mfma_f32_16x16x32_bf16 v[144:147], v[192:195], v[172:175], 0
	v_mfma_f32_16x16x32_bf16 v[148:151], v[180:183], v[176:179], 0
	v_mfma_f32_16x16x32_bf16 v[152:155], v[184:187], v[176:179], 0
	v_mfma_f32_16x16x32_bf16 v[156:159], v[188:191], v[176:179], 0
	v_mfma_f32_16x16x32_bf16 v[160:163], v[192:195], v[176:179], 0
	global_load_dwordx4 v[164:167], v6, s[36:37] offset:0
	global_load_dwordx4 v[168:171], v7, s[36:37] offset:0
	global_load_dwordx4 v[172:175], v8, s[36:37] offset:0
	global_load_dwordx4 v[176:179], v56, s[36:37] offset:0
	global_load_dwordx4 v[180:183], v6, s[66:67] offset:0
	global_load_dwordx4 v[184:187], v7, s[66:67] offset:0
	global_load_dwordx4 v[188:191], v8, s[66:67] offset:0
	global_load_dwordx4 v[192:195], v56, s[66:67] offset:0
	s_waitcnt vmcnt(24)
	ds_bpermute_b32 v12, v0, v12
	ds_bpermute_b32 v13, v0, v13
	ds_bpermute_b32 v14, v0, v14
	ds_bpermute_b32 v15, v0, v15
	ds_bpermute_b32 v16, v0, v16
	ds_bpermute_b32 v17, v0, v17
	ds_bpermute_b32 v18, v0, v18
	ds_bpermute_b32 v19, v0, v19
	ds_bpermute_b32 v20, v0, v20
	ds_bpermute_b32 v21, v0, v21
	ds_bpermute_b32 v22, v0, v22
	ds_bpermute_b32 v23, v0, v23
	ds_bpermute_b32 v24, v0, v24
	ds_bpermute_b32 v25, v0, v25
	ds_bpermute_b32 v26, v0, v26
	ds_bpermute_b32 v27, v0, v27
	ds_bpermute_b32 v28, v0, v28
	ds_bpermute_b32 v29, v0, v29
	ds_bpermute_b32 v30, v0, v30
	ds_bpermute_b32 v31, v0, v31
	ds_bpermute_b32 v32, v0, v32
	ds_bpermute_b32 v33, v0, v33
	ds_bpermute_b32 v34, v0, v34
	ds_bpermute_b32 v35, v0, v35
	ds_bpermute_b32 v36, v0, v36
	ds_bpermute_b32 v37, v0, v37
	ds_bpermute_b32 v38, v0, v38
	ds_bpermute_b32 v39, v0, v39
	ds_bpermute_b32 v40, v0, v40
	ds_bpermute_b32 v41, v0, v41
	ds_bpermute_b32 v42, v0, v42
	ds_bpermute_b32 v43, v0, v43
	s_waitcnt lgkmcnt(0)
	v_mfma_f32_16x16x32_bf16 v[100:103], v[28:31], v[12:15], v[100:103]
	v_mfma_f32_16x16x32_bf16 v[104:107], v[32:35], v[12:15], v[104:107]
	v_mfma_f32_16x16x32_bf16 v[108:111], v[36:39], v[12:15], v[108:111]
	v_mfma_f32_16x16x32_bf16 v[112:115], v[40:43], v[12:15], v[112:115]
	v_mfma_f32_16x16x32_bf16 v[116:119], v[28:31], v[16:19], v[116:119]
	v_mfma_f32_16x16x32_bf16 v[120:123], v[32:35], v[16:19], v[120:123]
	v_mfma_f32_16x16x32_bf16 v[124:127], v[36:39], v[16:19], v[124:127]
	v_mfma_f32_16x16x32_bf16 v[128:131], v[40:43], v[16:19], v[128:131]
	v_mfma_f32_16x16x32_bf16 v[132:135], v[28:31], v[20:23], v[132:135]
	v_mfma_f32_16x16x32_bf16 v[136:139], v[32:35], v[20:23], v[136:139]
	v_mfma_f32_16x16x32_bf16 v[140:143], v[36:39], v[20:23], v[140:143]
	v_mfma_f32_16x16x32_bf16 v[144:147], v[40:43], v[20:23], v[144:147]
	v_mfma_f32_16x16x32_bf16 v[148:151], v[28:31], v[24:27], v[148:151]
	v_mfma_f32_16x16x32_bf16 v[152:155], v[32:35], v[24:27], v[152:155]
	v_mfma_f32_16x16x32_bf16 v[156:159], v[36:39], v[24:27], v[156:159]
	v_mfma_f32_16x16x32_bf16 v[160:163], v[40:43], v[24:27], v[160:163]
	global_load_dwordx4 v[12:15], v6, s[36:37] offset:64
	global_load_dwordx4 v[16:19], v7, s[36:37] offset:64
	global_load_dwordx4 v[20:23], v8, s[36:37] offset:64
	global_load_dwordx4 v[24:27], v56, s[36:37] offset:64
	global_load_dwordx4 v[28:31], v6, s[66:67] offset:64
	global_load_dwordx4 v[32:35], v7, s[66:67] offset:64
	global_load_dwordx4 v[36:39], v8, s[66:67] offset:64
	global_load_dwordx4 v[40:43], v56, s[66:67] offset:64
	s_waitcnt vmcnt(24)
	ds_bpermute_b32 v60, v0, v60
	ds_bpermute_b32 v61, v0, v61
	ds_bpermute_b32 v62, v0, v62
	ds_bpermute_b32 v63, v0, v63
	ds_bpermute_b32 v64, v0, v64
	ds_bpermute_b32 v65, v0, v65
	ds_bpermute_b32 v66, v0, v66
	ds_bpermute_b32 v67, v0, v67
	ds_bpermute_b32 v68, v0, v68
	ds_bpermute_b32 v69, v0, v69
	ds_bpermute_b32 v70, v0, v70
	ds_bpermute_b32 v71, v0, v71
	ds_bpermute_b32 v72, v0, v72
	ds_bpermute_b32 v73, v0, v73
	ds_bpermute_b32 v74, v0, v74
	ds_bpermute_b32 v75, v0, v75
	ds_bpermute_b32 v76, v0, v76
	ds_bpermute_b32 v77, v0, v77
	ds_bpermute_b32 v78, v0, v78
	ds_bpermute_b32 v79, v0, v79
	ds_bpermute_b32 v80, v0, v80
	ds_bpermute_b32 v81, v0, v81
	ds_bpermute_b32 v82, v0, v82
	ds_bpermute_b32 v83, v0, v83
	ds_bpermute_b32 v84, v0, v84
	ds_bpermute_b32 v85, v0, v85
	ds_bpermute_b32 v86, v0, v86
	ds_bpermute_b32 v87, v0, v87
	ds_bpermute_b32 v88, v0, v88
	ds_bpermute_b32 v89, v0, v89
	ds_bpermute_b32 v90, v0, v90
	ds_bpermute_b32 v91, v0, v91
	s_waitcnt lgkmcnt(0)
	v_mfma_f32_16x16x32_bf16 v[100:103], v[76:79], v[60:63], v[100:103]
	v_mfma_f32_16x16x32_bf16 v[104:107], v[80:83], v[60:63], v[104:107]
	v_mfma_f32_16x16x32_bf16 v[108:111], v[84:87], v[60:63], v[108:111]
	v_mfma_f32_16x16x32_bf16 v[112:115], v[88:91], v[60:63], v[112:115]
	v_mfma_f32_16x16x32_bf16 v[116:119], v[76:79], v[64:67], v[116:119]
	v_mfma_f32_16x16x32_bf16 v[120:123], v[80:83], v[64:67], v[120:123]
	v_mfma_f32_16x16x32_bf16 v[124:127], v[84:87], v[64:67], v[124:127]
	v_mfma_f32_16x16x32_bf16 v[128:131], v[88:91], v[64:67], v[128:131]
	v_mfma_f32_16x16x32_bf16 v[132:135], v[76:79], v[68:71], v[132:135]
	v_mfma_f32_16x16x32_bf16 v[136:139], v[80:83], v[68:71], v[136:139]
	v_mfma_f32_16x16x32_bf16 v[140:143], v[84:87], v[68:71], v[140:143]
	v_mfma_f32_16x16x32_bf16 v[144:147], v[88:91], v[68:71], v[144:147]
	v_mfma_f32_16x16x32_bf16 v[148:151], v[76:79], v[72:75], v[148:151]
	v_mfma_f32_16x16x32_bf16 v[152:155], v[80:83], v[72:75], v[152:155]
	v_mfma_f32_16x16x32_bf16 v[156:159], v[84:87], v[72:75], v[156:159]
	v_mfma_f32_16x16x32_bf16 v[160:163], v[88:91], v[72:75], v[160:163]
	global_load_dwordx4 v[60:63], v6, s[36:37] offset:128
	global_load_dwordx4 v[64:67], v7, s[36:37] offset:128
	global_load_dwordx4 v[68:71], v8, s[36:37] offset:128
	global_load_dwordx4 v[72:75], v56, s[36:37] offset:128
	global_load_dwordx4 v[76:79], v6, s[66:67] offset:128
	global_load_dwordx4 v[80:83], v7, s[66:67] offset:128
	global_load_dwordx4 v[84:87], v8, s[66:67] offset:128
	global_load_dwordx4 v[88:91], v56, s[66:67] offset:128
	s_waitcnt vmcnt(24)
	ds_bpermute_b32 v196, v0, v196
	ds_bpermute_b32 v197, v0, v197
	ds_bpermute_b32 v198, v0, v198
	ds_bpermute_b32 v199, v0, v199
	ds_bpermute_b32 v200, v0, v200
	ds_bpermute_b32 v201, v0, v201
	ds_bpermute_b32 v202, v0, v202
	ds_bpermute_b32 v203, v0, v203
	ds_bpermute_b32 v204, v0, v204
	ds_bpermute_b32 v205, v0, v205
	ds_bpermute_b32 v206, v0, v206
	ds_bpermute_b32 v207, v0, v207
	ds_bpermute_b32 v208, v0, v208
	ds_bpermute_b32 v209, v0, v209
	ds_bpermute_b32 v210, v0, v210
	ds_bpermute_b32 v211, v0, v211
	ds_bpermute_b32 v212, v0, v212
	ds_bpermute_b32 v213, v0, v213
	ds_bpermute_b32 v214, v0, v214
	ds_bpermute_b32 v215, v0, v215
	ds_bpermute_b32 v44, v0, v44
	ds_bpermute_b32 v45, v0, v45
	ds_bpermute_b32 v46, v0, v46
	ds_bpermute_b32 v47, v0, v47
	ds_bpermute_b32 v48, v0, v48
	ds_bpermute_b32 v49, v0, v49
	ds_bpermute_b32 v50, v0, v50
	ds_bpermute_b32 v51, v0, v51
	ds_bpermute_b32 v52, v0, v52
	ds_bpermute_b32 v53, v0, v53
	ds_bpermute_b32 v54, v0, v54
	ds_bpermute_b32 v55, v0, v55
	s_waitcnt lgkmcnt(0)
	v_mfma_f32_16x16x32_bf16 v[100:103], v[212:215], v[196:199], v[100:103]
	v_mfma_f32_16x16x32_bf16 v[104:107], v[44:47], v[196:199], v[104:107]
	v_mfma_f32_16x16x32_bf16 v[108:111], v[48:51], v[196:199], v[108:111]
	v_mfma_f32_16x16x32_bf16 v[112:115], v[52:55], v[196:199], v[112:115]
	v_mfma_f32_16x16x32_bf16 v[116:119], v[212:215], v[200:203], v[116:119]
	v_mfma_f32_16x16x32_bf16 v[120:123], v[44:47], v[200:203], v[120:123]
	v_mfma_f32_16x16x32_bf16 v[124:127], v[48:51], v[200:203], v[124:127]
	v_mfma_f32_16x16x32_bf16 v[128:131], v[52:55], v[200:203], v[128:131]
	v_mfma_f32_16x16x32_bf16 v[132:135], v[212:215], v[204:207], v[132:135]
	v_mfma_f32_16x16x32_bf16 v[136:139], v[44:47], v[204:207], v[136:139]
	v_mfma_f32_16x16x32_bf16 v[140:143], v[48:51], v[204:207], v[140:143]
	v_mfma_f32_16x16x32_bf16 v[144:147], v[52:55], v[204:207], v[144:147]
	v_mfma_f32_16x16x32_bf16 v[148:151], v[212:215], v[208:211], v[148:151]
	v_mfma_f32_16x16x32_bf16 v[152:155], v[44:47], v[208:211], v[152:155]
	v_mfma_f32_16x16x32_bf16 v[156:159], v[48:51], v[208:211], v[156:159]
	v_mfma_f32_16x16x32_bf16 v[160:163], v[52:55], v[208:211], v[160:163]
	global_load_dwordx4 v[196:199], v6, s[36:37] offset:192
	global_load_dwordx4 v[200:203], v7, s[36:37] offset:192
	global_load_dwordx4 v[204:207], v8, s[36:37] offset:192
	global_load_dwordx4 v[208:211], v56, s[36:37] offset:192
	global_load_dwordx4 v[212:215], v6, s[66:67] offset:192
	global_load_dwordx4 v[44:47], v7, s[66:67] offset:192
	global_load_dwordx4 v[48:51], v8, s[66:67] offset:192
	global_load_dwordx4 v[52:55], v56, s[66:67] offset:192
	ds_write_b128 v57, v[100:103] offset:0
	ds_write_b128 v1, v[104:107] offset:0
	ds_write_b128 v234, v[108:111] offset:0
	ds_write_b128 v235, v[112:115] offset:0
	ds_write_b128 v57, v[116:119] offset:4096
	ds_write_b128 v1, v[120:123] offset:4096
	ds_write_b128 v234, v[124:127] offset:4096
	ds_write_b128 v235, v[128:131] offset:4096
	ds_write_b128 v57, v[132:135] offset:8192
	ds_write_b128 v1, v[136:139] offset:8192
	ds_write_b128 v234, v[140:143] offset:8192
	ds_write_b128 v235, v[144:147] offset:8192
	ds_write_b128 v57, v[148:151] offset:12288
	ds_write_b128 v1, v[152:155] offset:12288
	ds_write_b128 v234, v[156:159] offset:12288
	ds_write_b128 v235, v[160:163] offset:12288
	s_waitcnt lgkmcnt(0)
	s_barrier
	ds_read_b128 v[100:103], v59 offset:0
	ds_read_b128 v[104:107], v248 offset:0
	ds_read_b128 v[108:111], v59 offset:16384
	ds_read_b128 v[112:115], v248 offset:16384
	ds_read_b128 v[116:119], v59 offset:32768
	ds_read_b128 v[120:123], v248 offset:32768
	ds_read_b128 v[124:127], v59 offset:49152
	ds_read_b128 v[128:131], v248 offset:49152
	ds_read_b128 v[132:135], v98 offset:0
	ds_read_b128 v[136:139], v249 offset:0
	ds_read_b128 v[140:143], v98 offset:16384
	ds_read_b128 v[144:147], v249 offset:16384
	ds_read_b128 v[148:151], v98 offset:32768
	ds_read_b128 v[152:155], v249 offset:32768
	ds_read_b128 v[156:159], v98 offset:49152
	ds_read_b128 v[160:163], v249 offset:49152
	s_waitcnt lgkmcnt(0)
	s_barrier
	v_pk_add_f32 v[92:93], v[100:101], v[108:109]
	v_pk_add_f32 v[94:95], v[102:103], v[110:111]
	v_pk_add_f32 v[92:93], v[92:93], v[116:117]
	v_pk_add_f32 v[94:95], v[94:95], v[118:119]
	v_pk_add_f32 v[92:93], v[92:93], v[124:125]
	v_pk_add_f32 v[94:95], v[94:95], v[126:127]
	v_pk_add_f32 v[92:93], v[92:93], v[132:133]
	v_pk_add_f32 v[94:95], v[94:95], v[134:135]
	v_pk_add_f32 v[92:93], v[92:93], v[140:141]
	v_pk_add_f32 v[94:95], v[94:95], v[142:143]
	v_pk_add_f32 v[92:93], v[92:93], v[148:149]
	v_pk_add_f32 v[94:95], v[94:95], v[150:151]
	v_pk_add_f32 v[92:93], v[92:93], v[156:157]
	v_pk_add_f32 v[94:95], v[94:95], v[158:159]
	v_pk_add_f32 v[240:241], v[104:105], v[112:113]
	v_pk_add_f32 v[242:243], v[106:107], v[114:115]
	v_pk_add_f32 v[240:241], v[240:241], v[120:121]
	v_pk_add_f32 v[242:243], v[242:243], v[122:123]
	v_pk_add_f32 v[240:241], v[240:241], v[128:129]
	v_pk_add_f32 v[242:243], v[242:243], v[130:131]
	v_pk_add_f32 v[240:241], v[240:241], v[136:137]
	v_pk_add_f32 v[242:243], v[242:243], v[138:139]
	v_pk_add_f32 v[240:241], v[240:241], v[144:145]
	v_pk_add_f32 v[242:243], v[242:243], v[146:147]
	v_pk_add_f32 v[240:241], v[240:241], v[152:153]
	v_pk_add_f32 v[242:243], v[242:243], v[154:155]
	v_pk_add_f32 v[240:241], v[240:241], v[160:161]
	v_pk_add_f32 v[242:243], v[242:243], v[162:163]
	s_waitcnt vmcnt(24)
	ds_bpermute_b32 v164, v0, v164
	ds_bpermute_b32 v165, v0, v165
	ds_bpermute_b32 v166, v0, v166
	ds_bpermute_b32 v167, v0, v167
	ds_bpermute_b32 v168, v0, v168
	ds_bpermute_b32 v169, v0, v169
	ds_bpermute_b32 v170, v0, v170
	ds_bpermute_b32 v171, v0, v171
	ds_bpermute_b32 v172, v0, v172
	ds_bpermute_b32 v173, v0, v173
	ds_bpermute_b32 v174, v0, v174
	ds_bpermute_b32 v175, v0, v175
	ds_bpermute_b32 v176, v0, v176
	ds_bpermute_b32 v177, v0, v177
	ds_bpermute_b32 v178, v0, v178
	ds_bpermute_b32 v179, v0, v179
	ds_bpermute_b32 v180, v0, v180
	ds_bpermute_b32 v181, v0, v181
	ds_bpermute_b32 v182, v0, v182
	ds_bpermute_b32 v183, v0, v183
	ds_bpermute_b32 v184, v0, v184
	ds_bpermute_b32 v185, v0, v185
	ds_bpermute_b32 v186, v0, v186
	ds_bpermute_b32 v187, v0, v187
	ds_bpermute_b32 v188, v0, v188
	ds_bpermute_b32 v189, v0, v189
	ds_bpermute_b32 v190, v0, v190
	ds_bpermute_b32 v191, v0, v191
	ds_bpermute_b32 v192, v0, v192
	ds_bpermute_b32 v193, v0, v193
	ds_bpermute_b32 v194, v0, v194
	ds_bpermute_b32 v195, v0, v195
	s_waitcnt lgkmcnt(0)
	v_mfma_f32_16x16x32_bf16 v[100:103], v[180:183], v[164:167], 0
	v_mfma_f32_16x16x32_bf16 v[104:107], v[184:187], v[164:167], 0
	v_mfma_f32_16x16x32_bf16 v[108:111], v[188:191], v[164:167], 0
	v_mfma_f32_16x16x32_bf16 v[112:115], v[192:195], v[164:167], 0
	v_mfma_f32_16x16x32_bf16 v[116:119], v[180:183], v[168:171], 0
	v_mfma_f32_16x16x32_bf16 v[120:123], v[184:187], v[168:171], 0
	v_mfma_f32_16x16x32_bf16 v[124:127], v[188:191], v[168:171], 0
	v_mfma_f32_16x16x32_bf16 v[128:131], v[192:195], v[168:171], 0
	v_mfma_f32_16x16x32_bf16 v[132:135], v[180:183], v[172:175], 0
	v_mfma_f32_16x16x32_bf16 v[136:139], v[184:187], v[172:175], 0
	v_mfma_f32_16x16x32_bf16 v[140:143], v[188:191], v[172:175], 0
	v_mfma_f32_16x16x32_bf16 v[144:147], v[192:195], v[172:175], 0
	v_mfma_f32_16x16x32_bf16 v[148:151], v[180:183], v[176:179], 0
	v_mfma_f32_16x16x32_bf16 v[152:155], v[184:187], v[176:179], 0
	v_mfma_f32_16x16x32_bf16 v[156:159], v[188:191], v[176:179], 0
	v_mfma_f32_16x16x32_bf16 v[160:163], v[192:195], v[176:179], 0
	s_waitcnt vmcnt(16)
	ds_bpermute_b32 v12, v0, v12
	ds_bpermute_b32 v13, v0, v13
	ds_bpermute_b32 v14, v0, v14
	ds_bpermute_b32 v15, v0, v15
	ds_bpermute_b32 v16, v0, v16
	ds_bpermute_b32 v17, v0, v17
	ds_bpermute_b32 v18, v0, v18
	ds_bpermute_b32 v19, v0, v19
	ds_bpermute_b32 v20, v0, v20
	ds_bpermute_b32 v21, v0, v21
	ds_bpermute_b32 v22, v0, v22
	ds_bpermute_b32 v23, v0, v23
	ds_bpermute_b32 v24, v0, v24
	ds_bpermute_b32 v25, v0, v25
	ds_bpermute_b32 v26, v0, v26
	ds_bpermute_b32 v27, v0, v27
	ds_bpermute_b32 v28, v0, v28
	ds_bpermute_b32 v29, v0, v29
	ds_bpermute_b32 v30, v0, v30
	ds_bpermute_b32 v31, v0, v31
	ds_bpermute_b32 v32, v0, v32
	ds_bpermute_b32 v33, v0, v33
	ds_bpermute_b32 v34, v0, v34
	ds_bpermute_b32 v35, v0, v35
	ds_bpermute_b32 v36, v0, v36
	ds_bpermute_b32 v37, v0, v37
	ds_bpermute_b32 v38, v0, v38
	ds_bpermute_b32 v39, v0, v39
	ds_bpermute_b32 v40, v0, v40
	ds_bpermute_b32 v41, v0, v41
	ds_bpermute_b32 v42, v0, v42
	ds_bpermute_b32 v43, v0, v43
	s_waitcnt lgkmcnt(0)
	v_mfma_f32_16x16x32_bf16 v[100:103], v[28:31], v[12:15], v[100:103]
	v_mfma_f32_16x16x32_bf16 v[104:107], v[32:35], v[12:15], v[104:107]
	v_mfma_f32_16x16x32_bf16 v[108:111], v[36:39], v[12:15], v[108:111]
	v_mfma_f32_16x16x32_bf16 v[112:115], v[40:43], v[12:15], v[112:115]
	v_mfma_f32_16x16x32_bf16 v[116:119], v[28:31], v[16:19], v[116:119]
	v_mfma_f32_16x16x32_bf16 v[120:123], v[32:35], v[16:19], v[120:123]
	v_mfma_f32_16x16x32_bf16 v[124:127], v[36:39], v[16:19], v[124:127]
	v_mfma_f32_16x16x32_bf16 v[128:131], v[40:43], v[16:19], v[128:131]
	v_mfma_f32_16x16x32_bf16 v[132:135], v[28:31], v[20:23], v[132:135]
	v_mfma_f32_16x16x32_bf16 v[136:139], v[32:35], v[20:23], v[136:139]
	v_mfma_f32_16x16x32_bf16 v[140:143], v[36:39], v[20:23], v[140:143]
	v_mfma_f32_16x16x32_bf16 v[144:147], v[40:43], v[20:23], v[144:147]
	v_mfma_f32_16x16x32_bf16 v[148:151], v[28:31], v[24:27], v[148:151]
	v_mfma_f32_16x16x32_bf16 v[152:155], v[32:35], v[24:27], v[152:155]
	v_mfma_f32_16x16x32_bf16 v[156:159], v[36:39], v[24:27], v[156:159]
	v_mfma_f32_16x16x32_bf16 v[160:163], v[40:43], v[24:27], v[160:163]
	s_waitcnt vmcnt(8)
	ds_bpermute_b32 v60, v0, v60
	ds_bpermute_b32 v61, v0, v61
	ds_bpermute_b32 v62, v0, v62
	ds_bpermute_b32 v63, v0, v63
	ds_bpermute_b32 v64, v0, v64
	ds_bpermute_b32 v65, v0, v65
	ds_bpermute_b32 v66, v0, v66
	ds_bpermute_b32 v67, v0, v67
	ds_bpermute_b32 v68, v0, v68
	ds_bpermute_b32 v69, v0, v69
	ds_bpermute_b32 v70, v0, v70
	ds_bpermute_b32 v71, v0, v71
	ds_bpermute_b32 v72, v0, v72
	ds_bpermute_b32 v73, v0, v73
	ds_bpermute_b32 v74, v0, v74
	ds_bpermute_b32 v75, v0, v75
	ds_bpermute_b32 v76, v0, v76
	ds_bpermute_b32 v77, v0, v77
	ds_bpermute_b32 v78, v0, v78
	ds_bpermute_b32 v79, v0, v79
	ds_bpermute_b32 v80, v0, v80
	ds_bpermute_b32 v81, v0, v81
	ds_bpermute_b32 v82, v0, v82
	ds_bpermute_b32 v83, v0, v83
	ds_bpermute_b32 v84, v0, v84
	ds_bpermute_b32 v85, v0, v85
	ds_bpermute_b32 v86, v0, v86
	ds_bpermute_b32 v87, v0, v87
	ds_bpermute_b32 v88, v0, v88
	ds_bpermute_b32 v89, v0, v89
	ds_bpermute_b32 v90, v0, v90
	ds_bpermute_b32 v91, v0, v91
	s_waitcnt lgkmcnt(0)
	v_mfma_f32_16x16x32_bf16 v[100:103], v[76:79], v[60:63], v[100:103]
	v_mfma_f32_16x16x32_bf16 v[104:107], v[80:83], v[60:63], v[104:107]
	v_mfma_f32_16x16x32_bf16 v[108:111], v[84:87], v[60:63], v[108:111]
	v_mfma_f32_16x16x32_bf16 v[112:115], v[88:91], v[60:63], v[112:115]
	v_mfma_f32_16x16x32_bf16 v[116:119], v[76:79], v[64:67], v[116:119]
	v_mfma_f32_16x16x32_bf16 v[120:123], v[80:83], v[64:67], v[120:123]
	v_mfma_f32_16x16x32_bf16 v[124:127], v[84:87], v[64:67], v[124:127]
	v_mfma_f32_16x16x32_bf16 v[128:131], v[88:91], v[64:67], v[128:131]
	v_mfma_f32_16x16x32_bf16 v[132:135], v[76:79], v[68:71], v[132:135]
	v_mfma_f32_16x16x32_bf16 v[136:139], v[80:83], v[68:71], v[136:139]
	v_mfma_f32_16x16x32_bf16 v[140:143], v[84:87], v[68:71], v[140:143]
	v_mfma_f32_16x16x32_bf16 v[144:147], v[88:91], v[68:71], v[144:147]
	v_mfma_f32_16x16x32_bf16 v[148:151], v[76:79], v[72:75], v[148:151]
	v_mfma_f32_16x16x32_bf16 v[152:155], v[80:83], v[72:75], v[152:155]
	v_mfma_f32_16x16x32_bf16 v[156:159], v[84:87], v[72:75], v[156:159]
	v_mfma_f32_16x16x32_bf16 v[160:163], v[88:91], v[72:75], v[160:163]
	s_waitcnt vmcnt(0)
	ds_bpermute_b32 v196, v0, v196
	ds_bpermute_b32 v197, v0, v197
	ds_bpermute_b32 v198, v0, v198
	ds_bpermute_b32 v199, v0, v199
	ds_bpermute_b32 v200, v0, v200
	ds_bpermute_b32 v201, v0, v201
	ds_bpermute_b32 v202, v0, v202
	ds_bpermute_b32 v203, v0, v203
	ds_bpermute_b32 v204, v0, v204
	ds_bpermute_b32 v205, v0, v205
	ds_bpermute_b32 v206, v0, v206
	ds_bpermute_b32 v207, v0, v207
	ds_bpermute_b32 v208, v0, v208
	ds_bpermute_b32 v209, v0, v209
	ds_bpermute_b32 v210, v0, v210
	ds_bpermute_b32 v211, v0, v211
	ds_bpermute_b32 v212, v0, v212
	ds_bpermute_b32 v213, v0, v213
	ds_bpermute_b32 v214, v0, v214
	ds_bpermute_b32 v215, v0, v215
	ds_bpermute_b32 v44, v0, v44
	ds_bpermute_b32 v45, v0, v45
	ds_bpermute_b32 v46, v0, v46
	ds_bpermute_b32 v47, v0, v47
	ds_bpermute_b32 v48, v0, v48
	ds_bpermute_b32 v49, v0, v49
	ds_bpermute_b32 v50, v0, v50
	ds_bpermute_b32 v51, v0, v51
	ds_bpermute_b32 v52, v0, v52
	ds_bpermute_b32 v53, v0, v53
	ds_bpermute_b32 v54, v0, v54
	ds_bpermute_b32 v55, v0, v55
	s_waitcnt lgkmcnt(0)
	v_mfma_f32_16x16x32_bf16 v[100:103], v[212:215], v[196:199], v[100:103]
	v_mfma_f32_16x16x32_bf16 v[104:107], v[44:47], v[196:199], v[104:107]
	v_mfma_f32_16x16x32_bf16 v[108:111], v[48:51], v[196:199], v[108:111]
	v_mfma_f32_16x16x32_bf16 v[112:115], v[52:55], v[196:199], v[112:115]
	v_mfma_f32_16x16x32_bf16 v[116:119], v[212:215], v[200:203], v[116:119]
	v_mfma_f32_16x16x32_bf16 v[120:123], v[44:47], v[200:203], v[120:123]
	v_mfma_f32_16x16x32_bf16 v[124:127], v[48:51], v[200:203], v[124:127]
	v_mfma_f32_16x16x32_bf16 v[128:131], v[52:55], v[200:203], v[128:131]
	v_mfma_f32_16x16x32_bf16 v[132:135], v[212:215], v[204:207], v[132:135]
	v_mfma_f32_16x16x32_bf16 v[136:139], v[44:47], v[204:207], v[136:139]
	v_mfma_f32_16x16x32_bf16 v[140:143], v[48:51], v[204:207], v[140:143]
	v_mfma_f32_16x16x32_bf16 v[144:147], v[52:55], v[204:207], v[144:147]
	v_mfma_f32_16x16x32_bf16 v[148:151], v[212:215], v[208:211], v[148:151]
	v_mfma_f32_16x16x32_bf16 v[152:155], v[44:47], v[208:211], v[152:155]
	v_mfma_f32_16x16x32_bf16 v[156:159], v[48:51], v[208:211], v[156:159]
	v_mfma_f32_16x16x32_bf16 v[160:163], v[52:55], v[208:211], v[160:163]
	ds_write_b128 v57, v[100:103] offset:0
	ds_write_b128 v1, v[104:107] offset:0
	ds_write_b128 v234, v[108:111] offset:0
	ds_write_b128 v235, v[112:115] offset:0
	ds_write_b128 v57, v[116:119] offset:4096
	ds_write_b128 v1, v[120:123] offset:4096
	ds_write_b128 v234, v[124:127] offset:4096
	ds_write_b128 v235, v[128:131] offset:4096
	ds_write_b128 v57, v[132:135] offset:8192
	ds_write_b128 v1, v[136:139] offset:8192
	ds_write_b128 v234, v[140:143] offset:8192
	ds_write_b128 v235, v[144:147] offset:8192
	ds_write_b128 v57, v[148:151] offset:12288
	ds_write_b128 v1, v[152:155] offset:12288
	ds_write_b128 v234, v[156:159] offset:12288
	ds_write_b128 v235, v[160:163] offset:12288
	s_waitcnt lgkmcnt(0)
	s_barrier
	ds_read_b128 v[100:103], v59 offset:0
	ds_read_b128 v[104:107], v248 offset:0
	ds_read_b128 v[108:111], v59 offset:16384
	ds_read_b128 v[112:115], v248 offset:16384
	ds_read_b128 v[116:119], v59 offset:32768
	ds_read_b128 v[120:123], v248 offset:32768
	ds_read_b128 v[124:127], v59 offset:49152
	ds_read_b128 v[128:131], v248 offset:49152
	ds_read_b128 v[132:135], v98 offset:0
	ds_read_b128 v[136:139], v249 offset:0
	ds_read_b128 v[140:143], v98 offset:16384
	ds_read_b128 v[144:147], v249 offset:16384
	ds_read_b128 v[148:151], v98 offset:32768
	ds_read_b128 v[152:155], v249 offset:32768
	ds_read_b128 v[156:159], v98 offset:49152
	ds_read_b128 v[160:163], v249 offset:49152
	s_waitcnt lgkmcnt(0)
	s_barrier
	v_pk_add_f32 v[244:245], v[100:101], v[108:109]
	v_pk_add_f32 v[246:247], v[102:103], v[110:111]
	v_pk_add_f32 v[244:245], v[244:245], v[116:117]
	v_pk_add_f32 v[246:247], v[246:247], v[118:119]
	v_pk_add_f32 v[244:245], v[244:245], v[124:125]
	v_pk_add_f32 v[246:247], v[246:247], v[126:127]
	v_pk_add_f32 v[244:245], v[244:245], v[132:133]
	v_pk_add_f32 v[246:247], v[246:247], v[134:135]
	v_pk_add_f32 v[244:245], v[244:245], v[140:141]
	v_pk_add_f32 v[246:247], v[246:247], v[142:143]
	v_pk_add_f32 v[244:245], v[244:245], v[148:149]
	v_pk_add_f32 v[246:247], v[246:247], v[150:151]
	v_pk_add_f32 v[244:245], v[244:245], v[156:157]
	v_pk_add_f32 v[246:247], v[246:247], v[158:159]
	v_pk_add_f32 v[224:225], v[104:105], v[112:113]
	v_pk_add_f32 v[226:227], v[106:107], v[114:115]
	v_pk_add_f32 v[224:225], v[224:225], v[120:121]
	v_pk_add_f32 v[226:227], v[226:227], v[122:123]
	v_pk_add_f32 v[224:225], v[224:225], v[128:129]
	v_pk_add_f32 v[226:227], v[226:227], v[130:131]
	v_pk_add_f32 v[224:225], v[224:225], v[136:137]
	v_pk_add_f32 v[226:227], v[226:227], v[138:139]
	v_pk_add_f32 v[224:225], v[224:225], v[144:145]
	v_pk_add_f32 v[226:227], v[226:227], v[146:147]
	v_pk_add_f32 v[224:225], v[224:225], v[152:153]
	v_pk_add_f32 v[226:227], v[226:227], v[154:155]
	v_pk_add_f32 v[224:225], v[224:225], v[160:161]
	v_pk_add_f32 v[226:227], v[226:227], v[162:163]
	s_lshl_b32 s50, s7, 6
	s_sub_u32 s50, 0x110, s50
	v_cmp_gt_u32_e64 s[68:69], s50, v218
	s_and_saveexec_b64 s[48:49], s[68:69]
	s_cbranch_execz .Lsk_p3_done
	s_waitcnt vmcnt(0)
	v_lshlrev_b32_e32 v172, 16, v220
	v_and_b32_e32 v173, 0xffff0000, v220
	v_lshlrev_b32_e32 v174, 16, v221
	v_and_b32_e32 v175, 0xffff0000, v221
	v_lshlrev_b32_e32 v176, 16, v222
	v_and_b32_e32 v177, 0xffff0000, v222
	v_lshlrev_b32_e32 v178, 16, v223
	v_and_b32_e32 v179, 0xffff0000, v223
	v_cvt_f32_ubyte0_e32 v180, v238
	v_cvt_f32_ubyte1_e32 v181, v238
	v_cvt_f32_ubyte2_e32 v182, v238
	v_cvt_f32_ubyte3_e32 v183, v238
	v_cvt_f32_ubyte0_e32 v184, v239
	v_cvt_f32_ubyte1_e32 v185, v239
	v_cvt_f32_ubyte2_e32 v186, v239
	v_cvt_f32_ubyte3_e32 v187, v239
	v_mul_f32_e32 v180, 0x3b808081, v180
	v_mul_f32_e32 v181, 0x3b808081, v181
	v_mul_f32_e32 v182, 0x3b808081, v182
	v_mul_f32_e32 v183, 0x3b808081, v183
	v_mul_f32_e32 v184, 0x3b808081, v184
	v_mul_f32_e32 v185, 0x3b808081, v185
	v_mul_f32_e32 v186, 0x3b808081, v186
	v_mul_f32_e32 v187, 0x3b808081, v187
	v_fma_f32 v164, v172, v92, v244
	v_fma_f32 v165, v173, v93, v245
	v_fma_f32 v166, v174, v94, v246
	v_fma_f32 v167, v175, v95, v247
	v_fma_f32 v168, v176, v240, v224
	v_fma_f32 v169, v177, v241, v225
	v_fma_f32 v170, v178, v242, v226
	v_fma_f32 v171, v179, v243, v227
	v_mul_f32_e32 v164, v180, v164
	v_mul_f32_e32 v165, v181, v165
	v_mul_f32_e32 v166, v182, v166
	v_mul_f32_e32 v167, v183, v167
	v_mul_f32_e32 v168, v184, v168
	v_mul_f32_e32 v169, v185, v169
	v_mul_f32_e32 v170, v186, v170
	v_mul_f32_e32 v171, v187, v171
	v_cvt_pk_bf16_f32 v188, v164, v165
	v_cvt_pk_bf16_f32 v189, v166, v167
	v_cvt_pk_bf16_f32 v190, v168, v169
	v_cvt_pk_bf16_f32 v191, v170, v171
	s_nop 0
	global_store_dwordx4 v99, v[188:191], s[46:47]
.Lsk_p3_done:
	s_or_b64 exec, exec, s[48:49]

.LBB0_1712:
	v_readlane_b32 s4, v255, 19
	v_readlane_b32 s5, v255, 20
	s_waitcnt lgkmcnt(0)
	s_mov_b64 s[10:11], s[0:1]
	s_mov_b64 s[12:13], s[0:1]
	s_mov_b64 s[8:9], s[0:1]
	s_mov_b64 s[6:7], s[0:1]
	s_and_b64 vcc, exec, s[4:5]
	s_cbranch_vccnz .LBB0_1717
	s_load_dwordx2 s[4:5], s[0:1], 0xb0
	v_readlane_b32 s6, v253, 49
	v_readfirstlane_b32 s9, v219
	v_and_b32_e32 v196, 63, v219
	v_lshrrev_b32_e32 v218, 3, v219
	v_and_b32_e32 v228, 7, v219
	s_lshr_b32 s6, s6, 9
	s_lshr_b32 s9, s9, 6
	s_lshr_b32 s7, s6, 5
	s_and_b32 s8, s6, 31
	s_lshl_b32 s8, s8, 6
	v_and_b32_e32 v197, 15, v196
	v_lshrrev_b32_e32 v198, 4, v196
	v_lshrrev_b32_e32 v199, 2, v196
	v_and_b32_e32 v200, 3, v196
	v_lshlrev_b32_e32 v6, 12, v199
	v_lshl_add_u32 v6, v200, 4, v6
	v_add_u32_e32 v7, 0x10000, v6
	v_add_u32_e32 v8, 0x20000, v6
	v_add_u32_e32 v56, 0x30000, v6
	v_lshlrev_b32_e32 v0, 2, v198
	v_lshl_add_u32 v0, v197, 4, v0
	v_and_b32_e32 v201, 3, v197
	v_xor_b32_e32 v201, v201, v198
	v_lshrrev_b32_e32 v202, 2, v197
	v_lshlrev_b32_e32 v203, 8, v197
	s_lshl_b32 s50, s9, 14
	v_add_u32_e32 v203, s50, v203
	v_xor_b32_e32 v57, 0, v202
	v_lshl_add_u32 v57, v57, 2, v201
	v_lshl_add_u32 v57, v57, 4, v203
	v_xor_b32_e32 v1, 1, v202
	v_lshl_add_u32 v1, v1, 2, v201
	v_lshl_add_u32 v1, v1, 4, v203
	v_xor_b32_e32 v234, 2, v202
	v_lshl_add_u32 v234, v234, 2, v201
	v_lshl_add_u32 v234, v234, 4, v203
	v_xor_b32_e32 v235, 3, v202
	v_lshl_add_u32 v235, v235, 2, v201
	v_lshl_add_u32 v235, v235, 4, v203
	v_and_b32_e32 v196, 15, v218
	v_lshlrev_b32_e32 v197, 1, v228
	v_xor_b32_e32 v196, v196, v197
	v_lshlrev_b32_e32 v59, 8, v218
	v_lshl_add_u32 v59, v196, 4, v59
	v_xor_b32_e32 v248, 16, v59
	v_add_u32_e32 v98, 0x10000, v59
	v_add_u32_e32 v249, 0x10000, v248
	v_lshlrev_b32_e32 v99, 12, v218
	v_lshl_add_u32 v99, v228, 4, v99
	s_lshl_b32 s60, s7, 6
	s_add_u32 s60, s60, 0x2000
	s_lshl_b32 s50, s60, 12
	s_lshl_b32 s51, s9, 9
	s_add_u32 s50, s50, s51
	s_lshl_b32 s61, s8, 12
	s_add_u32 s61, s61, s51
	s_lshl_b32 s62, s90, 23
	s_lshl_b32 s63, s60, 11
	s_add_u32 s63, s63, s8
	s_waitcnt lgkmcnt(0)
	s_add_u32 s10, s4, 0x23900000
	s_addc_u32 s11, s5, 0
	s_add_u32 s10, s10, s50
	s_addc_u32 s11, s11, 0
	s_add_u32 s24, s4, 0x6400000
	s_addc_u32 s25, s5, 0
	s_add_u32 s24, s24, s62
	s_addc_u32 s25, s25, 0
	s_add_u32 s24, s24, s61
	s_addc_u32 s25, s25, 0
	s_lshl_b32 s64, s63, 1
	s_add_u32 s42, s4, 0x11800000
	s_addc_u32 s43, s5, 0
	s_add_u32 s42, s42, s64
	s_addc_u32 s43, s43, 0
	s_lshl_b32 s64, s90, 1
	s_add_u32 s64, s64, 1
	s_mul_i32 s64, s64, 0x110000
	s_lshl_b32 s65, s60, 5
	s_lshr_b32 s51, s8, 6
	s_add_u32 s65, s65, s51
	s_lshl_b32 s65, s65, 2
	s_add_u32 s64, s64, s65
	s_add_u32 s44, s4, 0x32800000
	s_addc_u32 s45, s5, 0
	s_add_u32 s44, s44, s64
	s_addc_u32 s45, s45, 0
	v_lshlrev_b32_e32 v231, 7, v218
	global_load_dwordx4 v[220:223], v99, s[42:43]
	global_load_dwordx4 v[164:167], v6, s[10:11] offset:0
	global_load_dwordx4 v[168:171], v7, s[10:11] offset:0
	global_load_dwordx4 v[172:175], v8, s[10:11] offset:0
	global_load_dwordx4 v[176:179], v56, s[10:11] offset:0
	global_load_dwordx4 v[180:183], v6, s[24:25] offset:0
	global_load_dwordx4 v[184:187], v7, s[24:25] offset:0
	global_load_dwordx4 v[188:191], v8, s[24:25] offset:0
	global_load_dwordx4 v[192:195], v56, s[24:25] offset:0
	global_load_dwordx4 v[12:15], v6, s[10:11] offset:64
	global_load_dwordx4 v[16:19], v7, s[10:11] offset:64
	global_load_dwordx4 v[20:23], v8, s[10:11] offset:64
	global_load_dwordx4 v[24:27], v56, s[10:11] offset:64
	global_load_dwordx4 v[28:31], v6, s[24:25] offset:64
	global_load_dwordx4 v[32:35], v7, s[24:25] offset:64
	global_load_dwordx4 v[36:39], v8, s[24:25] offset:64
	global_load_dwordx4 v[40:43], v56, s[24:25] offset:64
	global_load_dwordx4 v[60:63], v6, s[10:11] offset:128
	global_load_dwordx4 v[64:67], v7, s[10:11] offset:128
	global_load_dwordx4 v[68:71], v8, s[10:11] offset:128
	global_load_dwordx4 v[72:75], v56, s[10:11] offset:128
	global_load_dwordx4 v[76:79], v6, s[24:25] offset:128
	global_load_dwordx4 v[80:83], v7, s[24:25] offset:128
	global_load_dwordx4 v[84:87], v8, s[24:25] offset:128
	global_load_dwordx4 v[88:91], v56, s[24:25] offset:128
	global_load_dwordx4 v[196:199], v6, s[10:11] offset:192
	global_load_dwordx4 v[200:203], v7, s[10:11] offset:192
	global_load_dwordx4 v[204:207], v8, s[10:11] offset:192
	global_load_dwordx4 v[208:211], v56, s[10:11] offset:192
	global_load_dwordx4 v[212:215], v6, s[24:25] offset:192
	global_load_dwordx4 v[44:47], v7, s[24:25] offset:192
	global_load_dwordx4 v[48:51], v8, s[24:25] offset:192
	global_load_dwordx4 v[52:55], v56, s[24:25] offset:192
	s_waitcnt vmcnt(24)
	ds_bpermute_b32 v164, v0, v164
	ds_bpermute_b32 v165, v0, v165
	ds_bpermute_b32 v166, v0, v166
	ds_bpermute_b32 v167, v0, v167
	ds_bpermute_b32 v168, v0, v168
	ds_bpermute_b32 v169, v0, v169
	ds_bpermute_b32 v170, v0, v170
	ds_bpermute_b32 v171, v0, v171
	ds_bpermute_b32 v172, v0, v172
	ds_bpermute_b32 v173, v0, v173
	ds_bpermute_b32 v174, v0, v174
	ds_bpermute_b32 v175, v0, v175
	ds_bpermute_b32 v176, v0, v176
	ds_bpermute_b32 v177, v0, v177
	ds_bpermute_b32 v178, v0, v178
	ds_bpermute_b32 v179, v0, v179
	ds_bpermute_b32 v180, v0, v180
	ds_bpermute_b32 v181, v0, v181
	ds_bpermute_b32 v182, v0, v182
	ds_bpermute_b32 v183, v0, v183
	ds_bpermute_b32 v184, v0, v184
	ds_bpermute_b32 v185, v0, v185
	ds_bpermute_b32 v186, v0, v186
	ds_bpermute_b32 v187, v0, v187
	ds_bpermute_b32 v188, v0, v188
	ds_bpermute_b32 v189, v0, v189
	ds_bpermute_b32 v190, v0, v190
	ds_bpermute_b32 v191, v0, v191
	ds_bpermute_b32 v192, v0, v192
	ds_bpermute_b32 v193, v0, v193
	ds_bpermute_b32 v194, v0, v194
	ds_bpermute_b32 v195, v0, v195
	s_waitcnt lgkmcnt(0)
	v_mfma_f32_16x16x32_bf16 v[100:103], v[180:183], v[164:167], 0
	v_mfma_f32_16x16x32_bf16 v[104:107], v[184:187], v[164:167], 0
	v_mfma_f32_16x16x32_bf16 v[108:111], v[188:191], v[164:167], 0
	v_mfma_f32_16x16x32_bf16 v[112:115], v[192:195], v[164:167], 0
	v_mfma_f32_16x16x32_bf16 v[116:119], v[180:183], v[168:171], 0
	v_mfma_f32_16x16x32_bf16 v[120:123], v[184:187], v[168:171], 0
	v_mfma_f32_16x16x32_bf16 v[124:127], v[188:191], v[168:171], 0
	v_mfma_f32_16x16x32_bf16 v[128:131], v[192:195], v[168:171], 0
	v_mfma_f32_16x16x32_bf16 v[132:135], v[180:183], v[172:175], 0
	v_mfma_f32_16x16x32_bf16 v[136:139], v[184:187], v[172:175], 0
	v_mfma_f32_16x16x32_bf16 v[140:143], v[188:191], v[172:175], 0
	v_mfma_f32_16x16x32_bf16 v[144:147], v[192:195], v[172:175], 0
	v_mfma_f32_16x16x32_bf16 v[148:151], v[180:183], v[176:179], 0
	v_mfma_f32_16x16x32_bf16 v[152:155], v[184:187], v[176:179], 0
	v_mfma_f32_16x16x32_bf16 v[156:159], v[188:191], v[176:179], 0
	v_mfma_f32_16x16x32_bf16 v[160:163], v[192:195], v[176:179], 0
	global_load_dwordx4 v[164:167], v6, s[10:11] offset:256
	global_load_dwordx4 v[168:171], v7, s[10:11] offset:256
	global_load_dwordx4 v[172:175], v8, s[10:11] offset:256
	global_load_dwordx4 v[176:179], v56, s[10:11] offset:256
	global_load_dwordx4 v[180:183], v6, s[24:25] offset:256
	global_load_dwordx4 v[184:187], v7, s[24:25] offset:256
	global_load_dwordx4 v[188:191], v8, s[24:25] offset:256
	global_load_dwordx4 v[192:195], v56, s[24:25] offset:256
	s_waitcnt vmcnt(24)
	ds_bpermute_b32 v12, v0, v12
	ds_bpermute_b32 v13, v0, v13
	ds_bpermute_b32 v14, v0, v14
	ds_bpermute_b32 v15, v0, v15
	ds_bpermute_b32 v16, v0, v16
	ds_bpermute_b32 v17, v0, v17
	ds_bpermute_b32 v18, v0, v18
	ds_bpermute_b32 v19, v0, v19
	ds_bpermute_b32 v20, v0, v20
	ds_bpermute_b32 v21, v0, v21
	ds_bpermute_b32 v22, v0, v22
	ds_bpermute_b32 v23, v0, v23
	ds_bpermute_b32 v24, v0, v24
	ds_bpermute_b32 v25, v0, v25
	ds_bpermute_b32 v26, v0, v26
	ds_bpermute_b32 v27, v0, v27
	ds_bpermute_b32 v28, v0, v28
	ds_bpermute_b32 v29, v0, v29
	ds_bpermute_b32 v30, v0, v30
	ds_bpermute_b32 v31, v0, v31
	ds_bpermute_b32 v32, v0, v32
	ds_bpermute_b32 v33, v0, v33
	ds_bpermute_b32 v34, v0, v34
	ds_bpermute_b32 v35, v0, v35
	ds_bpermute_b32 v36, v0, v36
	ds_bpermute_b32 v37, v0, v37
	ds_bpermute_b32 v38, v0, v38
	ds_bpermute_b32 v39, v0, v39
	ds_bpermute_b32 v40, v0, v40
	ds_bpermute_b32 v41, v0, v41
	ds_bpermute_b32 v42, v0, v42
	ds_bpermute_b32 v43, v0, v43
	s_waitcnt lgkmcnt(0)
	v_mfma_f32_16x16x32_bf16 v[100:103], v[28:31], v[12:15], v[100:103]
	v_mfma_f32_16x16x32_bf16 v[104:107], v[32:35], v[12:15], v[104:107]
	v_mfma_f32_16x16x32_bf16 v[108:111], v[36:39], v[12:15], v[108:111]
	v_mfma_f32_16x16x32_bf16 v[112:115], v[40:43], v[12:15], v[112:115]
	v_mfma_f32_16x16x32_bf16 v[116:119], v[28:31], v[16:19], v[116:119]
	v_mfma_f32_16x16x32_bf16 v[120:123], v[32:35], v[16:19], v[120:123]
	v_mfma_f32_16x16x32_bf16 v[124:127], v[36:39], v[16:19], v[124:127]
	v_mfma_f32_16x16x32_bf16 v[128:131], v[40:43], v[16:19], v[128:131]
	v_mfma_f32_16x16x32_bf16 v[132:135], v[28:31], v[20:23], v[132:135]
	v_mfma_f32_16x16x32_bf16 v[136:139], v[32:35], v[20:23], v[136:139]
	v_mfma_f32_16x16x32_bf16 v[140:143], v[36:39], v[20:23], v[140:143]
	v_mfma_f32_16x16x32_bf16 v[144:147], v[40:43], v[20:23], v[144:147]
	v_mfma_f32_16x16x32_bf16 v[148:151], v[28:31], v[24:27], v[148:151]
	v_mfma_f32_16x16x32_bf16 v[152:155], v[32:35], v[24:27], v[152:155]
	v_mfma_f32_16x16x32_bf16 v[156:159], v[36:39], v[24:27], v[156:159]
	v_mfma_f32_16x16x32_bf16 v[160:163], v[40:43], v[24:27], v[160:163]
	global_load_dwordx4 v[12:15], v6, s[10:11] offset:320
	global_load_dwordx4 v[16:19], v7, s[10:11] offset:320
	global_load_dwordx4 v[20:23], v8, s[10:11] offset:320
	global_load_dwordx4 v[24:27], v56, s[10:11] offset:320
	global_load_dwordx4 v[28:31], v6, s[24:25] offset:320
	global_load_dwordx4 v[32:35], v7, s[24:25] offset:320
	global_load_dwordx4 v[36:39], v8, s[24:25] offset:320
	global_load_dwordx4 v[40:43], v56, s[24:25] offset:320
	s_waitcnt vmcnt(24)
	ds_bpermute_b32 v60, v0, v60
	ds_bpermute_b32 v61, v0, v61
	ds_bpermute_b32 v62, v0, v62
	ds_bpermute_b32 v63, v0, v63
	ds_bpermute_b32 v64, v0, v64
	ds_bpermute_b32 v65, v0, v65
	ds_bpermute_b32 v66, v0, v66
	ds_bpermute_b32 v67, v0, v67
	ds_bpermute_b32 v68, v0, v68
	ds_bpermute_b32 v69, v0, v69
	ds_bpermute_b32 v70, v0, v70
	ds_bpermute_b32 v71, v0, v71
	ds_bpermute_b32 v72, v0, v72
	ds_bpermute_b32 v73, v0, v73
	ds_bpermute_b32 v74, v0, v74
	ds_bpermute_b32 v75, v0, v75
	ds_bpermute_b32 v76, v0, v76
	ds_bpermute_b32 v77, v0, v77
	ds_bpermute_b32 v78, v0, v78
	ds_bpermute_b32 v79, v0, v79
	ds_bpermute_b32 v80, v0, v80
	ds_bpermute_b32 v81, v0, v81
	ds_bpermute_b32 v82, v0, v82
	ds_bpermute_b32 v83, v0, v83
	ds_bpermute_b32 v84, v0, v84
	ds_bpermute_b32 v85, v0, v85
	ds_bpermute_b32 v86, v0, v86
	ds_bpermute_b32 v87, v0, v87
	ds_bpermute_b32 v88, v0, v88
	ds_bpermute_b32 v89, v0, v89
	ds_bpermute_b32 v90, v0, v90
	ds_bpermute_b32 v91, v0, v91
	s_waitcnt lgkmcnt(0)
	v_mfma_f32_16x16x32_bf16 v[100:103], v[76:79], v[60:63], v[100:103]
	v_mfma_f32_16x16x32_bf16 v[104:107], v[80:83], v[60:63], v[104:107]
	v_mfma_f32_16x16x32_bf16 v[108:111], v[84:87], v[60:63], v[108:111]
	v_mfma_f32_16x16x32_bf16 v[112:115], v[88:91], v[60:63], v[112:115]
	v_mfma_f32_16x16x32_bf16 v[116:119], v[76:79], v[64:67], v[116:119]
	v_mfma_f32_16x16x32_bf16 v[120:123], v[80:83], v[64:67], v[120:123]
	v_mfma_f32_16x16x32_bf16 v[124:127], v[84:87], v[64:67], v[124:127]
	v_mfma_f32_16x16x32_bf16 v[128:131], v[88:91], v[64:67], v[128:131]
	v_mfma_f32_16x16x32_bf16 v[132:135], v[76:79], v[68:71], v[132:135]
	v_mfma_f32_16x16x32_bf16 v[136:139], v[80:83], v[68:71], v[136:139]
	v_mfma_f32_16x16x32_bf16 v[140:143], v[84:87], v[68:71], v[140:143]
	v_mfma_f32_16x16x32_bf16 v[144:147], v[88:91], v[68:71], v[144:147]
	v_mfma_f32_16x16x32_bf16 v[148:151], v[76:79], v[72:75], v[148:151]
	v_mfma_f32_16x16x32_bf16 v[152:155], v[80:83], v[72:75], v[152:155]
	v_mfma_f32_16x16x32_bf16 v[156:159], v[84:87], v[72:75], v[156:159]
	v_mfma_f32_16x16x32_bf16 v[160:163], v[88:91], v[72:75], v[160:163]
	global_load_dwordx4 v[60:63], v6, s[10:11] offset:384
	global_load_dwordx4 v[64:67], v7, s[10:11] offset:384
	global_load_dwordx4 v[68:71], v8, s[10:11] offset:384
	global_load_dwordx4 v[72:75], v56, s[10:11] offset:384
	global_load_dwordx4 v[76:79], v6, s[24:25] offset:384
	global_load_dwordx4 v[80:83], v7, s[24:25] offset:384
	global_load_dwordx4 v[84:87], v8, s[24:25] offset:384
	global_load_dwordx4 v[88:91], v56, s[24:25] offset:384
	s_waitcnt vmcnt(24)
	ds_bpermute_b32 v196, v0, v196
	ds_bpermute_b32 v197, v0, v197
	ds_bpermute_b32 v198, v0, v198
	ds_bpermute_b32 v199, v0, v199
	ds_bpermute_b32 v200, v0, v200
	ds_bpermute_b32 v201, v0, v201
	ds_bpermute_b32 v202, v0, v202
	ds_bpermute_b32 v203, v0, v203
	ds_bpermute_b32 v204, v0, v204
	ds_bpermute_b32 v205, v0, v205
	ds_bpermute_b32 v206, v0, v206
	ds_bpermute_b32 v207, v0, v207
	ds_bpermute_b32 v208, v0, v208
	ds_bpermute_b32 v209, v0, v209
	ds_bpermute_b32 v210, v0, v210
	ds_bpermute_b32 v211, v0, v211
	ds_bpermute_b32 v212, v0, v212
	ds_bpermute_b32 v213, v0, v213
	ds_bpermute_b32 v214, v0, v214
	ds_bpermute_b32 v215, v0, v215
	ds_bpermute_b32 v44, v0, v44
	ds_bpermute_b32 v45, v0, v45
	ds_bpermute_b32 v46, v0, v46
	ds_bpermute_b32 v47, v0, v47
	ds_bpermute_b32 v48, v0, v48
	ds_bpermute_b32 v49, v0, v49
	ds_bpermute_b32 v50, v0, v50
	ds_bpermute_b32 v51, v0, v51
	ds_bpermute_b32 v52, v0, v52
	ds_bpermute_b32 v53, v0, v53
	ds_bpermute_b32 v54, v0, v54
	ds_bpermute_b32 v55, v0, v55
	s_waitcnt lgkmcnt(0)
	v_mfma_f32_16x16x32_bf16 v[100:103], v[212:215], v[196:199], v[100:103]
	v_mfma_f32_16x16x32_bf16 v[104:107], v[44:47], v[196:199], v[104:107]
	v_mfma_f32_16x16x32_bf16 v[108:111], v[48:51], v[196:199], v[108:111]
	v_mfma_f32_16x16x32_bf16 v[112:115], v[52:55], v[196:199], v[112:115]
	v_mfma_f32_16x16x32_bf16 v[116:119], v[212:215], v[200:203], v[116:119]
	v_mfma_f32_16x16x32_bf16 v[120:123], v[44:47], v[200:203], v[120:123]
	v_mfma_f32_16x16x32_bf16 v[124:127], v[48:51], v[200:203], v[124:127]
	v_mfma_f32_16x16x32_bf16 v[128:131], v[52:55], v[200:203], v[128:131]
	v_mfma_f32_16x16x32_bf16 v[132:135], v[212:215], v[204:207], v[132:135]
	v_mfma_f32_16x16x32_bf16 v[136:139], v[44:47], v[204:207], v[136:139]
	v_mfma_f32_16x16x32_bf16 v[140:143], v[48:51], v[204:207], v[140:143]
	v_mfma_f32_16x16x32_bf16 v[144:147], v[52:55], v[204:207], v[144:147]
	v_mfma_f32_16x16x32_bf16 v[148:151], v[212:215], v[208:211], v[148:151]
	v_mfma_f32_16x16x32_bf16 v[152:155], v[44:47], v[208:211], v[152:155]
	v_mfma_f32_16x16x32_bf16 v[156:159], v[48:51], v[208:211], v[156:159]
	v_mfma_f32_16x16x32_bf16 v[160:163], v[52:55], v[208:211], v[160:163]
	global_load_dwordx4 v[196:199], v6, s[10:11] offset:448
	global_load_dwordx4 v[200:203], v7, s[10:11] offset:448
	global_load_dwordx4 v[204:207], v8, s[10:11] offset:448
	global_load_dwordx4 v[208:211], v56, s[10:11] offset:448
	global_load_dwordx4 v[212:215], v6, s[24:25] offset:448
	global_load_dwordx4 v[44:47], v7, s[24:25] offset:448
	global_load_dwordx4 v[48:51], v8, s[24:25] offset:448
	global_load_dwordx4 v[52:55], v56, s[24:25] offset:448
	s_waitcnt vmcnt(24)
	ds_bpermute_b32 v164, v0, v164
	ds_bpermute_b32 v165, v0, v165
	ds_bpermute_b32 v166, v0, v166
	ds_bpermute_b32 v167, v0, v167
	ds_bpermute_b32 v168, v0, v168
	ds_bpermute_b32 v169, v0, v169
	ds_bpermute_b32 v170, v0, v170
	ds_bpermute_b32 v171, v0, v171
	ds_bpermute_b32 v172, v0, v172
	ds_bpermute_b32 v173, v0, v173
	ds_bpermute_b32 v174, v0, v174
	ds_bpermute_b32 v175, v0, v175
	ds_bpermute_b32 v176, v0, v176
	ds_bpermute_b32 v177, v0, v177
	ds_bpermute_b32 v178, v0, v178
	ds_bpermute_b32 v179, v0, v179
	ds_bpermute_b32 v180, v0, v180
	ds_bpermute_b32 v181, v0, v181
	ds_bpermute_b32 v182, v0, v182
	ds_bpermute_b32 v183, v0, v183
	ds_bpermute_b32 v184, v0, v184
	ds_bpermute_b32 v185, v0, v185
	ds_bpermute_b32 v186, v0, v186
	ds_bpermute_b32 v187, v0, v187
	ds_bpermute_b32 v188, v0, v188
	ds_bpermute_b32 v189, v0, v189
	ds_bpermute_b32 v190, v0, v190
	ds_bpermute_b32 v191, v0, v191
	ds_bpermute_b32 v192, v0, v192
	ds_bpermute_b32 v193, v0, v193
	ds_bpermute_b32 v194, v0, v194
	ds_bpermute_b32 v195, v0, v195
	s_waitcnt lgkmcnt(0)
	v_mfma_f32_16x16x32_bf16 v[100:103], v[180:183], v[164:167], v[100:103]
	v_mfma_f32_16x16x32_bf16 v[104:107], v[184:187], v[164:167], v[104:107]
	v_mfma_f32_16x16x32_bf16 v[108:111], v[188:191], v[164:167], v[108:111]
	v_mfma_f32_16x16x32_bf16 v[112:115], v[192:195], v[164:167], v[112:115]
	v_mfma_f32_16x16x32_bf16 v[116:119], v[180:183], v[168:171], v[116:119]
	v_mfma_f32_16x16x32_bf16 v[120:123], v[184:187], v[168:171], v[120:123]
	v_mfma_f32_16x16x32_bf16 v[124:127], v[188:191], v[168:171], v[124:127]
	v_mfma_f32_16x16x32_bf16 v[128:131], v[192:195], v[168:171], v[128:131]
	v_mfma_f32_16x16x32_bf16 v[132:135], v[180:183], v[172:175], v[132:135]
	v_mfma_f32_16x16x32_bf16 v[136:139], v[184:187], v[172:175], v[136:139]
	v_mfma_f32_16x16x32_bf16 v[140:143], v[188:191], v[172:175], v[140:143]
	v_mfma_f32_16x16x32_bf16 v[144:147], v[192:195], v[172:175], v[144:147]
	v_mfma_f32_16x16x32_bf16 v[148:151], v[180:183], v[176:179], v[148:151]
	v_mfma_f32_16x16x32_bf16 v[152:155], v[184:187], v[176:179], v[152:155]
	v_mfma_f32_16x16x32_bf16 v[156:159], v[188:191], v[176:179], v[156:159]
	v_mfma_f32_16x16x32_bf16 v[160:163], v[192:195], v[176:179], v[160:163]
	s_waitcnt vmcnt(16)
	ds_bpermute_b32 v12, v0, v12
	ds_bpermute_b32 v13, v0, v13
	ds_bpermute_b32 v14, v0, v14
	ds_bpermute_b32 v15, v0, v15
	ds_bpermute_b32 v16, v0, v16
	ds_bpermute_b32 v17, v0, v17
	ds_bpermute_b32 v18, v0, v18
	ds_bpermute_b32 v19, v0, v19
	ds_bpermute_b32 v20, v0, v20
	ds_bpermute_b32 v21, v0, v21
	ds_bpermute_b32 v22, v0, v22
	ds_bpermute_b32 v23, v0, v23
	ds_bpermute_b32 v24, v0, v24
	ds_bpermute_b32 v25, v0, v25
	ds_bpermute_b32 v26, v0, v26
	ds_bpermute_b32 v27, v0, v27
	ds_bpermute_b32 v28, v0, v28
	ds_bpermute_b32 v29, v0, v29
	ds_bpermute_b32 v30, v0, v30
	ds_bpermute_b32 v31, v0, v31
	ds_bpermute_b32 v32, v0, v32
	ds_bpermute_b32 v33, v0, v33
	ds_bpermute_b32 v34, v0, v34
	ds_bpermute_b32 v35, v0, v35
	ds_bpermute_b32 v36, v0, v36
	ds_bpermute_b32 v37, v0, v37
	ds_bpermute_b32 v38, v0, v38
	ds_bpermute_b32 v39, v0, v39
	ds_bpermute_b32 v40, v0, v40
	ds_bpermute_b32 v41, v0, v41
	ds_bpermute_b32 v42, v0, v42
	ds_bpermute_b32 v43, v0, v43
	s_waitcnt lgkmcnt(0)
	v_mfma_f32_16x16x32_bf16 v[100:103], v[28:31], v[12:15], v[100:103]
	v_mfma_f32_16x16x32_bf16 v[104:107], v[32:35], v[12:15], v[104:107]
	v_mfma_f32_16x16x32_bf16 v[108:111], v[36:39], v[12:15], v[108:111]
	v_mfma_f32_16x16x32_bf16 v[112:115], v[40:43], v[12:15], v[112:115]
	v_mfma_f32_16x16x32_bf16 v[116:119], v[28:31], v[16:19], v[116:119]
	v_mfma_f32_16x16x32_bf16 v[120:123], v[32:35], v[16:19], v[120:123]
	v_mfma_f32_16x16x32_bf16 v[124:127], v[36:39], v[16:19], v[124:127]
	v_mfma_f32_16x16x32_bf16 v[128:131], v[40:43], v[16:19], v[128:131]
	v_mfma_f32_16x16x32_bf16 v[132:135], v[28:31], v[20:23], v[132:135]
	v_mfma_f32_16x16x32_bf16 v[136:139], v[32:35], v[20:23], v[136:139]
	v_mfma_f32_16x16x32_bf16 v[140:143], v[36:39], v[20:23], v[140:143]
	v_mfma_f32_16x16x32_bf16 v[144:147], v[40:43], v[20:23], v[144:147]
	v_mfma_f32_16x16x32_bf16 v[148:151], v[28:31], v[24:27], v[148:151]
	v_mfma_f32_16x16x32_bf16 v[152:155], v[32:35], v[24:27], v[152:155]
	v_mfma_f32_16x16x32_bf16 v[156:159], v[36:39], v[24:27], v[156:159]
	v_mfma_f32_16x16x32_bf16 v[160:163], v[40:43], v[24:27], v[160:163]
	s_waitcnt vmcnt(8)
	ds_bpermute_b32 v60, v0, v60
	ds_bpermute_b32 v61, v0, v61
	ds_bpermute_b32 v62, v0, v62
	ds_bpermute_b32 v63, v0, v63
	ds_bpermute_b32 v64, v0, v64
	ds_bpermute_b32 v65, v0, v65
	ds_bpermute_b32 v66, v0, v66
	ds_bpermute_b32 v67, v0, v67
	ds_bpermute_b32 v68, v0, v68
	ds_bpermute_b32 v69, v0, v69
	ds_bpermute_b32 v70, v0, v70
	ds_bpermute_b32 v71, v0, v71
	ds_bpermute_b32 v72, v0, v72
	ds_bpermute_b32 v73, v0, v73
	ds_bpermute_b32 v74, v0, v74
	ds_bpermute_b32 v75, v0, v75
	ds_bpermute_b32 v76, v0, v76
	ds_bpermute_b32 v77, v0, v77
	ds_bpermute_b32 v78, v0, v78
	ds_bpermute_b32 v79, v0, v79
	ds_bpermute_b32 v80, v0, v80
	ds_bpermute_b32 v81, v0, v81
	ds_bpermute_b32 v82, v0, v82
	ds_bpermute_b32 v83, v0, v83
	ds_bpermute_b32 v84, v0, v84
	ds_bpermute_b32 v85, v0, v85
	ds_bpermute_b32 v86, v0, v86
	ds_bpermute_b32 v87, v0, v87
	ds_bpermute_b32 v88, v0, v88
	ds_bpermute_b32 v89, v0, v89
	ds_bpermute_b32 v90, v0, v90
	ds_bpermute_b32 v91, v0, v91
	s_waitcnt lgkmcnt(0)
	v_mfma_f32_16x16x32_bf16 v[100:103], v[76:79], v[60:63], v[100:103]
	v_mfma_f32_16x16x32_bf16 v[104:107], v[80:83], v[60:63], v[104:107]
	v_mfma_f32_16x16x32_bf16 v[108:111], v[84:87], v[60:63], v[108:111]
	v_mfma_f32_16x16x32_bf16 v[112:115], v[88:91], v[60:63], v[112:115]
	v_mfma_f32_16x16x32_bf16 v[116:119], v[76:79], v[64:67], v[116:119]
	v_mfma_f32_16x16x32_bf16 v[120:123], v[80:83], v[64:67], v[120:123]
	v_mfma_f32_16x16x32_bf16 v[124:127], v[84:87], v[64:67], v[124:127]
	v_mfma_f32_16x16x32_bf16 v[128:131], v[88:91], v[64:67], v[128:131]
	v_mfma_f32_16x16x32_bf16 v[132:135], v[76:79], v[68:71], v[132:135]
	v_mfma_f32_16x16x32_bf16 v[136:139], v[80:83], v[68:71], v[136:139]
	v_mfma_f32_16x16x32_bf16 v[140:143], v[84:87], v[68:71], v[140:143]
	v_mfma_f32_16x16x32_bf16 v[144:147], v[88:91], v[68:71], v[144:147]
	v_mfma_f32_16x16x32_bf16 v[148:151], v[76:79], v[72:75], v[148:151]
	v_mfma_f32_16x16x32_bf16 v[152:155], v[80:83], v[72:75], v[152:155]
	v_mfma_f32_16x16x32_bf16 v[156:159], v[84:87], v[72:75], v[156:159]
	v_mfma_f32_16x16x32_bf16 v[160:163], v[88:91], v[72:75], v[160:163]
	s_waitcnt vmcnt(0)
	ds_bpermute_b32 v196, v0, v196
	ds_bpermute_b32 v197, v0, v197
	ds_bpermute_b32 v198, v0, v198
	ds_bpermute_b32 v199, v0, v199
	ds_bpermute_b32 v200, v0, v200
	ds_bpermute_b32 v201, v0, v201
	ds_bpermute_b32 v202, v0, v202
	ds_bpermute_b32 v203, v0, v203
	ds_bpermute_b32 v204, v0, v204
	ds_bpermute_b32 v205, v0, v205
	ds_bpermute_b32 v206, v0, v206
	ds_bpermute_b32 v207, v0, v207
	ds_bpermute_b32 v208, v0, v208
	ds_bpermute_b32 v209, v0, v209
	ds_bpermute_b32 v210, v0, v210
	ds_bpermute_b32 v211, v0, v211
	ds_bpermute_b32 v212, v0, v212
	ds_bpermute_b32 v213, v0, v213
	ds_bpermute_b32 v214, v0, v214
	ds_bpermute_b32 v215, v0, v215
	ds_bpermute_b32 v44, v0, v44
	ds_bpermute_b32 v45, v0, v45
	ds_bpermute_b32 v46, v0, v46
	ds_bpermute_b32 v47, v0, v47
	ds_bpermute_b32 v48, v0, v48
	ds_bpermute_b32 v49, v0, v49
	ds_bpermute_b32 v50, v0, v50
	ds_bpermute_b32 v51, v0, v51
	ds_bpermute_b32 v52, v0, v52
	ds_bpermute_b32 v53, v0, v53
	ds_bpermute_b32 v54, v0, v54
	ds_bpermute_b32 v55, v0, v55
	s_waitcnt lgkmcnt(0)
	v_mfma_f32_16x16x32_bf16 v[100:103], v[212:215], v[196:199], v[100:103]
	v_mfma_f32_16x16x32_bf16 v[104:107], v[44:47], v[196:199], v[104:107]
	v_mfma_f32_16x16x32_bf16 v[108:111], v[48:51], v[196:199], v[108:111]
	v_mfma_f32_16x16x32_bf16 v[112:115], v[52:55], v[196:199], v[112:115]
	v_mfma_f32_16x16x32_bf16 v[116:119], v[212:215], v[200:203], v[116:119]
	v_mfma_f32_16x16x32_bf16 v[120:123], v[44:47], v[200:203], v[120:123]
	v_mfma_f32_16x16x32_bf16 v[124:127], v[48:51], v[200:203], v[124:127]
	v_mfma_f32_16x16x32_bf16 v[128:131], v[52:55], v[200:203], v[128:131]
	v_mfma_f32_16x16x32_bf16 v[132:135], v[212:215], v[204:207], v[132:135]
	v_mfma_f32_16x16x32_bf16 v[136:139], v[44:47], v[204:207], v[136:139]
	v_mfma_f32_16x16x32_bf16 v[140:143], v[48:51], v[204:207], v[140:143]
	v_mfma_f32_16x16x32_bf16 v[144:147], v[52:55], v[204:207], v[144:147]
	v_mfma_f32_16x16x32_bf16 v[148:151], v[212:215], v[208:211], v[148:151]
	v_mfma_f32_16x16x32_bf16 v[152:155], v[44:47], v[208:211], v[152:155]
	v_mfma_f32_16x16x32_bf16 v[156:159], v[48:51], v[208:211], v[156:159]
	v_mfma_f32_16x16x32_bf16 v[160:163], v[52:55], v[208:211], v[160:163]
	ds_write_b128 v57, v[100:103] offset:0
	ds_write_b128 v1, v[104:107] offset:0
	ds_write_b128 v234, v[108:111] offset:0
	ds_write_b128 v235, v[112:115] offset:0
	ds_write_b128 v57, v[116:119] offset:4096
	ds_write_b128 v1, v[120:123] offset:4096
	ds_write_b128 v234, v[124:127] offset:4096
	ds_write_b128 v235, v[128:131] offset:4096
	ds_write_b128 v57, v[132:135] offset:8192
	ds_write_b128 v1, v[136:139] offset:8192
	ds_write_b128 v234, v[140:143] offset:8192
	ds_write_b128 v235, v[144:147] offset:8192
	ds_write_b128 v57, v[148:151] offset:12288
	ds_write_b128 v1, v[152:155] offset:12288
	ds_write_b128 v234, v[156:159] offset:12288
	ds_write_b128 v235, v[160:163] offset:12288
	s_waitcnt lgkmcnt(0)
	s_barrier
	ds_read_b128 v[100:103], v59 offset:0
	ds_read_b128 v[104:107], v248 offset:0
	ds_read_b128 v[108:111], v59 offset:16384
	ds_read_b128 v[112:115], v248 offset:16384
	ds_read_b128 v[116:119], v59 offset:32768
	ds_read_b128 v[120:123], v248 offset:32768
	ds_read_b128 v[124:127], v59 offset:49152
	ds_read_b128 v[128:131], v248 offset:49152
	ds_read_b128 v[132:135], v98 offset:0
	ds_read_b128 v[136:139], v249 offset:0
	ds_read_b128 v[140:143], v98 offset:16384
	ds_read_b128 v[144:147], v249 offset:16384
	ds_read_b128 v[148:151], v98 offset:32768
	ds_read_b128 v[152:155], v249 offset:32768
	ds_read_b128 v[156:159], v98 offset:49152
	ds_read_b128 v[160:163], v249 offset:49152
	s_waitcnt lgkmcnt(0)
	s_barrier
	v_pk_add_f32 v[244:245], v[100:101], v[108:109]
	v_pk_add_f32 v[246:247], v[102:103], v[110:111]
	v_pk_add_f32 v[244:245], v[244:245], v[116:117]
	v_pk_add_f32 v[246:247], v[246:247], v[118:119]
	v_pk_add_f32 v[244:245], v[244:245], v[124:125]
	v_pk_add_f32 v[246:247], v[246:247], v[126:127]
	v_pk_add_f32 v[244:245], v[244:245], v[132:133]
	v_pk_add_f32 v[246:247], v[246:247], v[134:135]
	v_pk_add_f32 v[244:245], v[244:245], v[140:141]
	v_pk_add_f32 v[246:247], v[246:247], v[142:143]
	v_pk_add_f32 v[244:245], v[244:245], v[148:149]
	v_pk_add_f32 v[246:247], v[246:247], v[150:151]
	v_pk_add_f32 v[244:245], v[244:245], v[156:157]
	v_pk_add_f32 v[246:247], v[246:247], v[158:159]
	v_pk_add_f32 v[224:225], v[104:105], v[112:113]
	v_pk_add_f32 v[226:227], v[106:107], v[114:115]
	v_pk_add_f32 v[224:225], v[224:225], v[120:121]
	v_pk_add_f32 v[226:227], v[226:227], v[122:123]
	v_pk_add_f32 v[224:225], v[224:225], v[128:129]
	v_pk_add_f32 v[226:227], v[226:227], v[130:131]
	v_pk_add_f32 v[224:225], v[224:225], v[136:137]
	v_pk_add_f32 v[226:227], v[226:227], v[138:139]
	v_pk_add_f32 v[224:225], v[224:225], v[144:145]
	v_pk_add_f32 v[226:227], v[226:227], v[146:147]
	v_pk_add_f32 v[224:225], v[224:225], v[152:153]
	v_pk_add_f32 v[226:227], v[226:227], v[154:155]
	v_pk_add_f32 v[224:225], v[224:225], v[160:161]
	v_pk_add_f32 v[226:227], v[226:227], v[162:163]
	s_lshl_b32 s50, s7, 6
	s_sub_u32 s50, 0x110, s50
	v_cmp_gt_u32_e64 s[46:47], s50, v218
	s_and_saveexec_b64 s[48:49], s[46:47]
	s_cbranch_execz .Lsk_p4_done
	s_waitcnt vmcnt(0)
	v_lshlrev_b32_e32 v164, 16, v220
	v_and_b32_e32 v165, 0xffff0000, v220
	v_lshlrev_b32_e32 v166, 16, v221
	v_and_b32_e32 v167, 0xffff0000, v221
	v_lshlrev_b32_e32 v168, 16, v222
	v_and_b32_e32 v169, 0xffff0000, v222
	v_lshlrev_b32_e32 v170, 16, v223
	v_and_b32_e32 v171, 0xffff0000, v223
	v_add_f32_e32 v164, v164, v244
	v_add_f32_e32 v165, v165, v245
	v_add_f32_e32 v166, v166, v246
	v_add_f32_e32 v167, v167, v247
	v_add_f32_e32 v168, v168, v224
	v_add_f32_e32 v169, v169, v225
	v_add_f32_e32 v170, v170, v226
	v_add_f32_e32 v171, v171, v227
	v_cvt_pk_bf16_f32 v188, v164, v165
	v_cvt_pk_bf16_f32 v189, v166, v167
	v_cvt_pk_bf16_f32 v190, v168, v169
	v_cvt_pk_bf16_f32 v191, v170, v171
	s_nop 0
	global_store_dwordx4 v99, v[188:191], s[42:43]
	v_mul_f32_e32 v176, v164, v164
	v_mul_f32_e32 v177, v166, v166
	v_fmac_f32_e32 v176, v165, v165
	v_fmac_f32_e32 v177, v167, v167
	v_add_f32_e32 v176, v176, v177
	v_mul_f32_e32 v177, v168, v168
	v_mul_f32_e32 v178, v170, v170
	v_fmac_f32_e32 v177, v169, v169
	v_fmac_f32_e32 v178, v171, v171
	v_add_f32_e32 v177, v177, v178
	v_add_f32_e32 v176, v176, v177
	s_nop 1
	v_add_f32_dpp v176, v176, v176 quad_perm:[1,0,3,2] row_mask:0xf bank_mask:0xf bound_ctrl:1
	s_nop 1
	v_add_f32_dpp v176, v176, v176 quad_perm:[2,3,0,1] row_mask:0xf bank_mask:0xf bound_ctrl:1
	s_nop 1
	v_add_f32_dpp v176, v176, v176 row_shr:4 row_mask:0xf bank_mask:0xf bound_ctrl:1
	v_cmp_eq_u32_e64 s[46:47], 7, v228
	s_and_b64 exec, exec, s[46:47]
	global_store_dword v231, v176, s[44:45]

.LBB0_2412:
	v_readlane_b32 s4, v255, 19
	v_readlane_b32 s5, v255, 20
	s_waitcnt lgkmcnt(0)
	s_mov_b64 s[6:7], s[0:1]
	s_mov_b64 s[8:9], s[0:1]
	s_mov_b64 s[12:13], s[0:1]
	s_mov_b64 s[14:15], s[0:1]
	s_and_b64 vcc, exec, s[4:5]
	s_cbranch_vccnz .LBB0_2419
	s_load_dwordx2 s[4:5], s[0:1], 0xb0
	v_readlane_b32 s6, v253, 49
	v_readfirstlane_b32 s9, v219
	v_and_b32_e32 v196, 63, v219
	v_lshrrev_b32_e32 v218, 3, v219
	v_and_b32_e32 v228, 7, v219
	s_lshr_b32 s6, s6, 9
	s_lshr_b32 s9, s9, 6
	s_lshr_b32 s7, s6, 5
	s_and_b32 s8, s6, 31
	s_lshl_b32 s8, s8, 6
	v_and_b32_e32 v197, 15, v196
	v_lshrrev_b32_e32 v198, 4, v196
	v_lshrrev_b32_e32 v199, 2, v196
	v_and_b32_e32 v200, 3, v196
	v_lshlrev_b32_e32 v6, 13, v199
	v_lshl_add_u32 v6, v200, 4, v6
	v_add_u32_e32 v7, 0x20000, v6
	v_add_u32_e32 v8, 0x40000, v6
	v_add_u32_e32 v56, 0x60000, v6
	v_lshlrev_b32_e32 v0, 2, v198
	v_lshl_add_u32 v0, v197, 4, v0
	v_and_b32_e32 v201, 3, v197
	v_xor_b32_e32 v201, v201, v198
	v_lshrrev_b32_e32 v202, 2, v197
	v_lshlrev_b32_e32 v203, 8, v197
	s_lshl_b32 s50, s9, 14
	v_add_u32_e32 v203, s50, v203
	v_xor_b32_e32 v57, 0, v202
	v_lshl_add_u32 v57, v57, 2, v201
	v_lshl_add_u32 v57, v57, 4, v203
	v_xor_b32_e32 v1, 1, v202
	v_lshl_add_u32 v1, v1, 2, v201
	v_lshl_add_u32 v1, v1, 4, v203
	v_xor_b32_e32 v234, 2, v202
	v_lshl_add_u32 v234, v234, 2, v201
	v_lshl_add_u32 v234, v234, 4, v203
	v_xor_b32_e32 v235, 3, v202
	v_lshl_add_u32 v235, v235, 2, v201
	v_lshl_add_u32 v235, v235, 4, v203
	v_and_b32_e32 v196, 15, v218
	v_lshlrev_b32_e32 v197, 1, v228
	v_xor_b32_e32 v196, v196, v197
	v_lshlrev_b32_e32 v59, 8, v218
	v_lshl_add_u32 v59, v196, 4, v59
	v_xor_b32_e32 v248, 16, v59
	v_add_u32_e32 v98, 0x10000, v59
	v_add_u32_e32 v249, 0x10000, v248
	v_lshlrev_b32_e32 v99, 12, v218
	v_lshl_add_u32 v99, v228, 4, v99
	s_lshl_b32 s60, s7, 6
	s_add_u32 s60, s60, 0x2000
	s_lshl_b32 s50, s60, 13
	s_lshl_b32 s51, s9, 10
	s_add_u32 s50, s50, s51
	s_lshl_b32 s61, s8, 13
	s_add_u32 s61, s61, s51
	s_lshl_b32 s62, s90, 24
	s_lshl_b32 s63, s60, 11
	s_add_u32 s63, s63, s8
	s_waitcnt lgkmcnt(0)
	s_add_u32 s10, s4, 0x2e300000
	s_addc_u32 s11, s5, 0
	s_add_u32 s10, s10, s50
	s_addc_u32 s11, s11, 0
	s_add_u32 s24, s4, 0xb400000
	s_addc_u32 s25, s5, 0
	s_add_u32 s24, s24, s62
	s_addc_u32 s25, s25, 0
	s_add_u32 s24, s24, s61
	s_addc_u32 s25, s25, 0
	s_lshl_b32 s64, s63, 1
	s_add_u32 s42, s4, 0x11800000
	s_addc_u32 s43, s5, 0
	s_add_u32 s42, s42, s64
	s_addc_u32 s43, s43, 0
	s_lshl_b32 s64, s90, 1
	s_add_u32 s64, s64, 2
	s_mul_i32 s64, s64, 0x110000
	s_lshl_b32 s65, s60, 5
	s_lshr_b32 s51, s8, 6
	s_add_u32 s65, s65, s51
	s_lshl_b32 s65, s65, 2
	s_add_u32 s64, s64, s65
	s_add_u32 s44, s4, 0x32800000
	s_addc_u32 s45, s5, 0
	s_add_u32 s44, s44, s64
	s_addc_u32 s45, s45, 0
	v_lshlrev_b32_e32 v231, 7, v218
	global_load_dwordx4 v[220:223], v99, s[42:43]
	global_load_dwordx4 v[164:167], v6, s[10:11] offset:0
	global_load_dwordx4 v[168:171], v7, s[10:11] offset:0
	global_load_dwordx4 v[172:175], v8, s[10:11] offset:0
	global_load_dwordx4 v[176:179], v56, s[10:11] offset:0
	global_load_dwordx4 v[180:183], v6, s[24:25] offset:0
	global_load_dwordx4 v[184:187], v7, s[24:25] offset:0
	global_load_dwordx4 v[188:191], v8, s[24:25] offset:0
	global_load_dwordx4 v[192:195], v56, s[24:25] offset:0
	global_load_dwordx4 v[12:15], v6, s[10:11] offset:64
	global_load_dwordx4 v[16:19], v7, s[10:11] offset:64
	global_load_dwordx4 v[20:23], v8, s[10:11] offset:64
	global_load_dwordx4 v[24:27], v56, s[10:11] offset:64
	global_load_dwordx4 v[28:31], v6, s[24:25] offset:64
	global_load_dwordx4 v[32:35], v7, s[24:25] offset:64
	global_load_dwordx4 v[36:39], v8, s[24:25] offset:64
	global_load_dwordx4 v[40:43], v56, s[24:25] offset:64
	global_load_dwordx4 v[60:63], v6, s[10:11] offset:128
	global_load_dwordx4 v[64:67], v7, s[10:11] offset:128
	global_load_dwordx4 v[68:71], v8, s[10:11] offset:128
	global_load_dwordx4 v[72:75], v56, s[10:11] offset:128
	global_load_dwordx4 v[76:79], v6, s[24:25] offset:128
	global_load_dwordx4 v[80:83], v7, s[24:25] offset:128
	global_load_dwordx4 v[84:87], v8, s[24:25] offset:128
	global_load_dwordx4 v[88:91], v56, s[24:25] offset:128
	global_load_dwordx4 v[196:199], v6, s[10:11] offset:192
	global_load_dwordx4 v[200:203], v7, s[10:11] offset:192
	global_load_dwordx4 v[204:207], v8, s[10:11] offset:192
	global_load_dwordx4 v[208:211], v56, s[10:11] offset:192
	global_load_dwordx4 v[212:215], v6, s[24:25] offset:192
	global_load_dwordx4 v[44:47], v7, s[24:25] offset:192
	global_load_dwordx4 v[48:51], v8, s[24:25] offset:192
	global_load_dwordx4 v[52:55], v56, s[24:25] offset:192
	s_waitcnt vmcnt(24)
	ds_bpermute_b32 v164, v0, v164
	ds_bpermute_b32 v165, v0, v165
	ds_bpermute_b32 v166, v0, v166
	ds_bpermute_b32 v167, v0, v167
	ds_bpermute_b32 v168, v0, v168
	ds_bpermute_b32 v169, v0, v169
	ds_bpermute_b32 v170, v0, v170
	ds_bpermute_b32 v171, v0, v171
	ds_bpermute_b32 v172, v0, v172
	ds_bpermute_b32 v173, v0, v173
	ds_bpermute_b32 v174, v0, v174
	ds_bpermute_b32 v175, v0, v175
	ds_bpermute_b32 v176, v0, v176
	ds_bpermute_b32 v177, v0, v177
	ds_bpermute_b32 v178, v0, v178
	ds_bpermute_b32 v179, v0, v179
	ds_bpermute_b32 v180, v0, v180
	ds_bpermute_b32 v181, v0, v181
	ds_bpermute_b32 v182, v0, v182
	ds_bpermute_b32 v183, v0, v183
	ds_bpermute_b32 v184, v0, v184
	ds_bpermute_b32 v185, v0, v185
	ds_bpermute_b32 v186, v0, v186
	ds_bpermute_b32 v187, v0, v187
	ds_bpermute_b32 v188, v0, v188
	ds_bpermute_b32 v189, v0, v189
	ds_bpermute_b32 v190, v0, v190
	ds_bpermute_b32 v191, v0, v191
	ds_bpermute_b32 v192, v0, v192
	ds_bpermute_b32 v193, v0, v193
	ds_bpermute_b32 v194, v0, v194
	ds_bpermute_b32 v195, v0, v195
	s_waitcnt lgkmcnt(0)
	v_mfma_f32_16x16x32_bf16 v[100:103], v[180:183], v[164:167], 0
	v_mfma_f32_16x16x32_bf16 v[104:107], v[184:187], v[164:167], 0
	v_mfma_f32_16x16x32_bf16 v[108:111], v[188:191], v[164:167], 0
	v_mfma_f32_16x16x32_bf16 v[112:115], v[192:195], v[164:167], 0
	v_mfma_f32_16x16x32_bf16 v[116:119], v[180:183], v[168:171], 0
	v_mfma_f32_16x16x32_bf16 v[120:123], v[184:187], v[168:171], 0
	v_mfma_f32_16x16x32_bf16 v[124:127], v[188:191], v[168:171], 0
	v_mfma_f32_16x16x32_bf16 v[128:131], v[192:195], v[168:171], 0
	v_mfma_f32_16x16x32_bf16 v[132:135], v[180:183], v[172:175], 0
	v_mfma_f32_16x16x32_bf16 v[136:139], v[184:187], v[172:175], 0
	v_mfma_f32_16x16x32_bf16 v[140:143], v[188:191], v[172:175], 0
	v_mfma_f32_16x16x32_bf16 v[144:147], v[192:195], v[172:175], 0
	v_mfma_f32_16x16x32_bf16 v[148:151], v[180:183], v[176:179], 0
	v_mfma_f32_16x16x32_bf16 v[152:155], v[184:187], v[176:179], 0
	v_mfma_f32_16x16x32_bf16 v[156:159], v[188:191], v[176:179], 0
	v_mfma_f32_16x16x32_bf16 v[160:163], v[192:195], v[176:179], 0
	global_load_dwordx4 v[164:167], v6, s[10:11] offset:256
	global_load_dwordx4 v[168:171], v7, s[10:11] offset:256
	global_load_dwordx4 v[172:175], v8, s[10:11] offset:256
	global_load_dwordx4 v[176:179], v56, s[10:11] offset:256
	global_load_dwordx4 v[180:183], v6, s[24:25] offset:256
	global_load_dwordx4 v[184:187], v7, s[24:25] offset:256
	global_load_dwordx4 v[188:191], v8, s[24:25] offset:256
	global_load_dwordx4 v[192:195], v56, s[24:25] offset:256
	s_waitcnt vmcnt(24)
	ds_bpermute_b32 v12, v0, v12
	ds_bpermute_b32 v13, v0, v13
	ds_bpermute_b32 v14, v0, v14
	ds_bpermute_b32 v15, v0, v15
	ds_bpermute_b32 v16, v0, v16
	ds_bpermute_b32 v17, v0, v17
	ds_bpermute_b32 v18, v0, v18
	ds_bpermute_b32 v19, v0, v19
	ds_bpermute_b32 v20, v0, v20
	ds_bpermute_b32 v21, v0, v21
	ds_bpermute_b32 v22, v0, v22
	ds_bpermute_b32 v23, v0, v23
	ds_bpermute_b32 v24, v0, v24
	ds_bpermute_b32 v25, v0, v25
	ds_bpermute_b32 v26, v0, v26
	ds_bpermute_b32 v27, v0, v27
	ds_bpermute_b32 v28, v0, v28
	ds_bpermute_b32 v29, v0, v29
	ds_bpermute_b32 v30, v0, v30
	ds_bpermute_b32 v31, v0, v31
	ds_bpermute_b32 v32, v0, v32
	ds_bpermute_b32 v33, v0, v33
	ds_bpermute_b32 v34, v0, v34
	ds_bpermute_b32 v35, v0, v35
	ds_bpermute_b32 v36, v0, v36
	ds_bpermute_b32 v37, v0, v37
	ds_bpermute_b32 v38, v0, v38
	ds_bpermute_b32 v39, v0, v39
	ds_bpermute_b32 v40, v0, v40
	ds_bpermute_b32 v41, v0, v41
	ds_bpermute_b32 v42, v0, v42
	ds_bpermute_b32 v43, v0, v43
	s_waitcnt lgkmcnt(0)
	v_mfma_f32_16x16x32_bf16 v[100:103], v[28:31], v[12:15], v[100:103]
	v_mfma_f32_16x16x32_bf16 v[104:107], v[32:35], v[12:15], v[104:107]
	v_mfma_f32_16x16x32_bf16 v[108:111], v[36:39], v[12:15], v[108:111]
	v_mfma_f32_16x16x32_bf16 v[112:115], v[40:43], v[12:15], v[112:115]
	v_mfma_f32_16x16x32_bf16 v[116:119], v[28:31], v[16:19], v[116:119]
	v_mfma_f32_16x16x32_bf16 v[120:123], v[32:35], v[16:19], v[120:123]
	v_mfma_f32_16x16x32_bf16 v[124:127], v[36:39], v[16:19], v[124:127]
	v_mfma_f32_16x16x32_bf16 v[128:131], v[40:43], v[16:19], v[128:131]
	v_mfma_f32_16x16x32_bf16 v[132:135], v[28:31], v[20:23], v[132:135]
	v_mfma_f32_16x16x32_bf16 v[136:139], v[32:35], v[20:23], v[136:139]
	v_mfma_f32_16x16x32_bf16 v[140:143], v[36:39], v[20:23], v[140:143]
	v_mfma_f32_16x16x32_bf16 v[144:147], v[40:43], v[20:23], v[144:147]
	v_mfma_f32_16x16x32_bf16 v[148:151], v[28:31], v[24:27], v[148:151]
	v_mfma_f32_16x16x32_bf16 v[152:155], v[32:35], v[24:27], v[152:155]
	v_mfma_f32_16x16x32_bf16 v[156:159], v[36:39], v[24:27], v[156:159]
	v_mfma_f32_16x16x32_bf16 v[160:163], v[40:43], v[24:27], v[160:163]
	global_load_dwordx4 v[12:15], v6, s[10:11] offset:320
	global_load_dwordx4 v[16:19], v7, s[10:11] offset:320
	global_load_dwordx4 v[20:23], v8, s[10:11] offset:320
	global_load_dwordx4 v[24:27], v56, s[10:11] offset:320
	global_load_dwordx4 v[28:31], v6, s[24:25] offset:320
	global_load_dwordx4 v[32:35], v7, s[24:25] offset:320
	global_load_dwordx4 v[36:39], v8, s[24:25] offset:320
	global_load_dwordx4 v[40:43], v56, s[24:25] offset:320
	s_waitcnt vmcnt(24)
	ds_bpermute_b32 v60, v0, v60
	ds_bpermute_b32 v61, v0, v61
	ds_bpermute_b32 v62, v0, v62
	ds_bpermute_b32 v63, v0, v63
	ds_bpermute_b32 v64, v0, v64
	ds_bpermute_b32 v65, v0, v65
	ds_bpermute_b32 v66, v0, v66
	ds_bpermute_b32 v67, v0, v67
	ds_bpermute_b32 v68, v0, v68
	ds_bpermute_b32 v69, v0, v69
	ds_bpermute_b32 v70, v0, v70
	ds_bpermute_b32 v71, v0, v71
	ds_bpermute_b32 v72, v0, v72
	ds_bpermute_b32 v73, v0, v73
	ds_bpermute_b32 v74, v0, v74
	ds_bpermute_b32 v75, v0, v75
	ds_bpermute_b32 v76, v0, v76
	ds_bpermute_b32 v77, v0, v77
	ds_bpermute_b32 v78, v0, v78
	ds_bpermute_b32 v79, v0, v79
	ds_bpermute_b32 v80, v0, v80
	ds_bpermute_b32 v81, v0, v81
	ds_bpermute_b32 v82, v0, v82
	ds_bpermute_b32 v83, v0, v83
	ds_bpermute_b32 v84, v0, v84
	ds_bpermute_b32 v85, v0, v85
	ds_bpermute_b32 v86, v0, v86
	ds_bpermute_b32 v87, v0, v87
	ds_bpermute_b32 v88, v0, v88
	ds_bpermute_b32 v89, v0, v89
	ds_bpermute_b32 v90, v0, v90
	ds_bpermute_b32 v91, v0, v91
	s_waitcnt lgkmcnt(0)
	v_mfma_f32_16x16x32_bf16 v[100:103], v[76:79], v[60:63], v[100:103]
	v_mfma_f32_16x16x32_bf16 v[104:107], v[80:83], v[60:63], v[104:107]
	v_mfma_f32_16x16x32_bf16 v[108:111], v[84:87], v[60:63], v[108:111]
	v_mfma_f32_16x16x32_bf16 v[112:115], v[88:91], v[60:63], v[112:115]
	v_mfma_f32_16x16x32_bf16 v[116:119], v[76:79], v[64:67], v[116:119]
	v_mfma_f32_16x16x32_bf16 v[120:123], v[80:83], v[64:67], v[120:123]
	v_mfma_f32_16x16x32_bf16 v[124:127], v[84:87], v[64:67], v[124:127]
	v_mfma_f32_16x16x32_bf16 v[128:131], v[88:91], v[64:67], v[128:131]
	v_mfma_f32_16x16x32_bf16 v[132:135], v[76:79], v[68:71], v[132:135]
	v_mfma_f32_16x16x32_bf16 v[136:139], v[80:83], v[68:71], v[136:139]
	v_mfma_f32_16x16x32_bf16 v[140:143], v[84:87], v[68:71], v[140:143]
	v_mfma_f32_16x16x32_bf16 v[144:147], v[88:91], v[68:71], v[144:147]
	v_mfma_f32_16x16x32_bf16 v[148:151], v[76:79], v[72:75], v[148:151]
	v_mfma_f32_16x16x32_bf16 v[152:155], v[80:83], v[72:75], v[152:155]
	v_mfma_f32_16x16x32_bf16 v[156:159], v[84:87], v[72:75], v[156:159]
	v_mfma_f32_16x16x32_bf16 v[160:163], v[88:91], v[72:75], v[160:163]
	global_load_dwordx4 v[60:63], v6, s[10:11] offset:384
	global_load_dwordx4 v[64:67], v7, s[10:11] offset:384
	global_load_dwordx4 v[68:71], v8, s[10:11] offset:384
	global_load_dwordx4 v[72:75], v56, s[10:11] offset:384
	global_load_dwordx4 v[76:79], v6, s[24:25] offset:384
	global_load_dwordx4 v[80:83], v7, s[24:25] offset:384
	global_load_dwordx4 v[84:87], v8, s[24:25] offset:384
	global_load_dwordx4 v[88:91], v56, s[24:25] offset:384
	s_waitcnt vmcnt(24)
	ds_bpermute_b32 v196, v0, v196
	ds_bpermute_b32 v197, v0, v197
	ds_bpermute_b32 v198, v0, v198
	ds_bpermute_b32 v199, v0, v199
	ds_bpermute_b32 v200, v0, v200
	ds_bpermute_b32 v201, v0, v201
	ds_bpermute_b32 v202, v0, v202
	ds_bpermute_b32 v203, v0, v203
	ds_bpermute_b32 v204, v0, v204
	ds_bpermute_b32 v205, v0, v205
	ds_bpermute_b32 v206, v0, v206
	ds_bpermute_b32 v207, v0, v207
	ds_bpermute_b32 v208, v0, v208
	ds_bpermute_b32 v209, v0, v209
	ds_bpermute_b32 v210, v0, v210
	ds_bpermute_b32 v211, v0, v211
	ds_bpermute_b32 v212, v0, v212
	ds_bpermute_b32 v213, v0, v213
	ds_bpermute_b32 v214, v0, v214
	ds_bpermute_b32 v215, v0, v215
	ds_bpermute_b32 v44, v0, v44
	ds_bpermute_b32 v45, v0, v45
	ds_bpermute_b32 v46, v0, v46
	ds_bpermute_b32 v47, v0, v47
	ds_bpermute_b32 v48, v0, v48
	ds_bpermute_b32 v49, v0, v49
	ds_bpermute_b32 v50, v0, v50
	ds_bpermute_b32 v51, v0, v51
	ds_bpermute_b32 v52, v0, v52
	ds_bpermute_b32 v53, v0, v53
	ds_bpermute_b32 v54, v0, v54
	ds_bpermute_b32 v55, v0, v55
	s_waitcnt lgkmcnt(0)
	v_mfma_f32_16x16x32_bf16 v[100:103], v[212:215], v[196:199], v[100:103]
	v_mfma_f32_16x16x32_bf16 v[104:107], v[44:47], v[196:199], v[104:107]
	v_mfma_f32_16x16x32_bf16 v[108:111], v[48:51], v[196:199], v[108:111]
	v_mfma_f32_16x16x32_bf16 v[112:115], v[52:55], v[196:199], v[112:115]
	v_mfma_f32_16x16x32_bf16 v[116:119], v[212:215], v[200:203], v[116:119]
	v_mfma_f32_16x16x32_bf16 v[120:123], v[44:47], v[200:203], v[120:123]
	v_mfma_f32_16x16x32_bf16 v[124:127], v[48:51], v[200:203], v[124:127]
	v_mfma_f32_16x16x32_bf16 v[128:131], v[52:55], v[200:203], v[128:131]
	v_mfma_f32_16x16x32_bf16 v[132:135], v[212:215], v[204:207], v[132:135]
	v_mfma_f32_16x16x32_bf16 v[136:139], v[44:47], v[204:207], v[136:139]
	v_mfma_f32_16x16x32_bf16 v[140:143], v[48:51], v[204:207], v[140:143]
	v_mfma_f32_16x16x32_bf16 v[144:147], v[52:55], v[204:207], v[144:147]
	v_mfma_f32_16x16x32_bf16 v[148:151], v[212:215], v[208:211], v[148:151]
	v_mfma_f32_16x16x32_bf16 v[152:155], v[44:47], v[208:211], v[152:155]
	v_mfma_f32_16x16x32_bf16 v[156:159], v[48:51], v[208:211], v[156:159]
	v_mfma_f32_16x16x32_bf16 v[160:163], v[52:55], v[208:211], v[160:163]
	global_load_dwordx4 v[196:199], v6, s[10:11] offset:448
	global_load_dwordx4 v[200:203], v7, s[10:11] offset:448
	global_load_dwordx4 v[204:207], v8, s[10:11] offset:448
	global_load_dwordx4 v[208:211], v56, s[10:11] offset:448
	global_load_dwordx4 v[212:215], v6, s[24:25] offset:448
	global_load_dwordx4 v[44:47], v7, s[24:25] offset:448
	global_load_dwordx4 v[48:51], v8, s[24:25] offset:448
	global_load_dwordx4 v[52:55], v56, s[24:25] offset:448
	s_waitcnt vmcnt(24)
	ds_bpermute_b32 v164, v0, v164
	ds_bpermute_b32 v165, v0, v165
	ds_bpermute_b32 v166, v0, v166
	ds_bpermute_b32 v167, v0, v167
	ds_bpermute_b32 v168, v0, v168
	ds_bpermute_b32 v169, v0, v169
	ds_bpermute_b32 v170, v0, v170
	ds_bpermute_b32 v171, v0, v171
	ds_bpermute_b32 v172, v0, v172
	ds_bpermute_b32 v173, v0, v173
	ds_bpermute_b32 v174, v0, v174
	ds_bpermute_b32 v175, v0, v175
	ds_bpermute_b32 v176, v0, v176
	ds_bpermute_b32 v177, v0, v177
	ds_bpermute_b32 v178, v0, v178
	ds_bpermute_b32 v179, v0, v179
	ds_bpermute_b32 v180, v0, v180
	ds_bpermute_b32 v181, v0, v181
	ds_bpermute_b32 v182, v0, v182
	ds_bpermute_b32 v183, v0, v183
	ds_bpermute_b32 v184, v0, v184
	ds_bpermute_b32 v185, v0, v185
	ds_bpermute_b32 v186, v0, v186
	ds_bpermute_b32 v187, v0, v187
	ds_bpermute_b32 v188, v0, v188
	ds_bpermute_b32 v189, v0, v189
	ds_bpermute_b32 v190, v0, v190
	ds_bpermute_b32 v191, v0, v191
	ds_bpermute_b32 v192, v0, v192
	ds_bpermute_b32 v193, v0, v193
	ds_bpermute_b32 v194, v0, v194
	ds_bpermute_b32 v195, v0, v195
	s_waitcnt lgkmcnt(0)
	v_mfma_f32_16x16x32_bf16 v[100:103], v[180:183], v[164:167], v[100:103]
	v_mfma_f32_16x16x32_bf16 v[104:107], v[184:187], v[164:167], v[104:107]
	v_mfma_f32_16x16x32_bf16 v[108:111], v[188:191], v[164:167], v[108:111]
	v_mfma_f32_16x16x32_bf16 v[112:115], v[192:195], v[164:167], v[112:115]
	v_mfma_f32_16x16x32_bf16 v[116:119], v[180:183], v[168:171], v[116:119]
	v_mfma_f32_16x16x32_bf16 v[120:123], v[184:187], v[168:171], v[120:123]
	v_mfma_f32_16x16x32_bf16 v[124:127], v[188:191], v[168:171], v[124:127]
	v_mfma_f32_16x16x32_bf16 v[128:131], v[192:195], v[168:171], v[128:131]
	v_mfma_f32_16x16x32_bf16 v[132:135], v[180:183], v[172:175], v[132:135]
	v_mfma_f32_16x16x32_bf16 v[136:139], v[184:187], v[172:175], v[136:139]
	v_mfma_f32_16x16x32_bf16 v[140:143], v[188:191], v[172:175], v[140:143]
	v_mfma_f32_16x16x32_bf16 v[144:147], v[192:195], v[172:175], v[144:147]
	v_mfma_f32_16x16x32_bf16 v[148:151], v[180:183], v[176:179], v[148:151]
	v_mfma_f32_16x16x32_bf16 v[152:155], v[184:187], v[176:179], v[152:155]
	v_mfma_f32_16x16x32_bf16 v[156:159], v[188:191], v[176:179], v[156:159]
	v_mfma_f32_16x16x32_bf16 v[160:163], v[192:195], v[176:179], v[160:163]
	global_load_dwordx4 v[164:167], v6, s[10:11] offset:512
	global_load_dwordx4 v[168:171], v7, s[10:11] offset:512
	global_load_dwordx4 v[172:175], v8, s[10:11] offset:512
	global_load_dwordx4 v[176:179], v56, s[10:11] offset:512
	global_load_dwordx4 v[180:183], v6, s[24:25] offset:512
	global_load_dwordx4 v[184:187], v7, s[24:25] offset:512
	global_load_dwordx4 v[188:191], v8, s[24:25] offset:512
	global_load_dwordx4 v[192:195], v56, s[24:25] offset:512
	s_waitcnt vmcnt(24)
	ds_bpermute_b32 v12, v0, v12
	ds_bpermute_b32 v13, v0, v13
	ds_bpermute_b32 v14, v0, v14
	ds_bpermute_b32 v15, v0, v15
	ds_bpermute_b32 v16, v0, v16
	ds_bpermute_b32 v17, v0, v17
	ds_bpermute_b32 v18, v0, v18
	ds_bpermute_b32 v19, v0, v19
	ds_bpermute_b32 v20, v0, v20
	ds_bpermute_b32 v21, v0, v21
	ds_bpermute_b32 v22, v0, v22
	ds_bpermute_b32 v23, v0, v23
	ds_bpermute_b32 v24, v0, v24
	ds_bpermute_b32 v25, v0, v25
	ds_bpermute_b32 v26, v0, v26
	ds_bpermute_b32 v27, v0, v27
	ds_bpermute_b32 v28, v0, v28
	ds_bpermute_b32 v29, v0, v29
	ds_bpermute_b32 v30, v0, v30
	ds_bpermute_b32 v31, v0, v31
	ds_bpermute_b32 v32, v0, v32
	ds_bpermute_b32 v33, v0, v33
	ds_bpermute_b32 v34, v0, v34
	ds_bpermute_b32 v35, v0, v35
	ds_bpermute_b32 v36, v0, v36
	ds_bpermute_b32 v37, v0, v37
	ds_bpermute_b32 v38, v0, v38
	ds_bpermute_b32 v39, v0, v39
	ds_bpermute_b32 v40, v0, v40
	ds_bpermute_b32 v41, v0, v41
	ds_bpermute_b32 v42, v0, v42
	ds_bpermute_b32 v43, v0, v43
	s_waitcnt lgkmcnt(0)
	v_mfma_f32_16x16x32_bf16 v[100:103], v[28:31], v[12:15], v[100:103]
	v_mfma_f32_16x16x32_bf16 v[104:107], v[32:35], v[12:15], v[104:107]
	v_mfma_f32_16x16x32_bf16 v[108:111], v[36:39], v[12:15], v[108:111]
	v_mfma_f32_16x16x32_bf16 v[112:115], v[40:43], v[12:15], v[112:115]
	v_mfma_f32_16x16x32_bf16 v[116:119], v[28:31], v[16:19], v[116:119]
	v_mfma_f32_16x16x32_bf16 v[120:123], v[32:35], v[16:19], v[120:123]
	v_mfma_f32_16x16x32_bf16 v[124:127], v[36:39], v[16:19], v[124:127]
	v_mfma_f32_16x16x32_bf16 v[128:131], v[40:43], v[16:19], v[128:131]
	v_mfma_f32_16x16x32_bf16 v[132:135], v[28:31], v[20:23], v[132:135]
	v_mfma_f32_16x16x32_bf16 v[136:139], v[32:35], v[20:23], v[136:139]
	v_mfma_f32_16x16x32_bf16 v[140:143], v[36:39], v[20:23], v[140:143]
	v_mfma_f32_16x16x32_bf16 v[144:147], v[40:43], v[20:23], v[144:147]
	v_mfma_f32_16x16x32_bf16 v[148:151], v[28:31], v[24:27], v[148:151]
	v_mfma_f32_16x16x32_bf16 v[152:155], v[32:35], v[24:27], v[152:155]
	v_mfma_f32_16x16x32_bf16 v[156:159], v[36:39], v[24:27], v[156:159]
	v_mfma_f32_16x16x32_bf16 v[160:163], v[40:43], v[24:27], v[160:163]
	global_load_dwordx4 v[12:15], v6, s[10:11] offset:576
	global_load_dwordx4 v[16:19], v7, s[10:11] offset:576
	global_load_dwordx4 v[20:23], v8, s[10:11] offset:576
	global_load_dwordx4 v[24:27], v56, s[10:11] offset:576
	global_load_dwordx4 v[28:31], v6, s[24:25] offset:576
	global_load_dwordx4 v[32:35], v7, s[24:25] offset:576
	global_load_dwordx4 v[36:39], v8, s[24:25] offset:576
	global_load_dwordx4 v[40:43], v56, s[24:25] offset:576
	s_waitcnt vmcnt(24)
	ds_bpermute_b32 v60, v0, v60
	ds_bpermute_b32 v61, v0, v61
	ds_bpermute_b32 v62, v0, v62
	ds_bpermute_b32 v63, v0, v63
	ds_bpermute_b32 v64, v0, v64
	ds_bpermute_b32 v65, v0, v65
	ds_bpermute_b32 v66, v0, v66
	ds_bpermute_b32 v67, v0, v67
	ds_bpermute_b32 v68, v0, v68
	ds_bpermute_b32 v69, v0, v69
	ds_bpermute_b32 v70, v0, v70
	ds_bpermute_b32 v71, v0, v71
	ds_bpermute_b32 v72, v0, v72
	ds_bpermute_b32 v73, v0, v73
	ds_bpermute_b32 v74, v0, v74
	ds_bpermute_b32 v75, v0, v75
	ds_bpermute_b32 v76, v0, v76
	ds_bpermute_b32 v77, v0, v77
	ds_bpermute_b32 v78, v0, v78
	ds_bpermute_b32 v79, v0, v79
	ds_bpermute_b32 v80, v0, v80
	ds_bpermute_b32 v81, v0, v81
	ds_bpermute_b32 v82, v0, v82
	ds_bpermute_b32 v83, v0, v83
	ds_bpermute_b32 v84, v0, v84
	ds_bpermute_b32 v85, v0, v85
	ds_bpermute_b32 v86, v0, v86
	ds_bpermute_b32 v87, v0, v87
	ds_bpermute_b32 v88, v0, v88
	ds_bpermute_b32 v89, v0, v89
	ds_bpermute_b32 v90, v0, v90
	ds_bpermute_b32 v91, v0, v91
	s_waitcnt lgkmcnt(0)
	v_mfma_f32_16x16x32_bf16 v[100:103], v[76:79], v[60:63], v[100:103]
	v_mfma_f32_16x16x32_bf16 v[104:107], v[80:83], v[60:63], v[104:107]
	v_mfma_f32_16x16x32_bf16 v[108:111], v[84:87], v[60:63], v[108:111]
	v_mfma_f32_16x16x32_bf16 v[112:115], v[88:91], v[60:63], v[112:115]
	v_mfma_f32_16x16x32_bf16 v[116:119], v[76:79], v[64:67], v[116:119]
	v_mfma_f32_16x16x32_bf16 v[120:123], v[80:83], v[64:67], v[120:123]
	v_mfma_f32_16x16x32_bf16 v[124:127], v[84:87], v[64:67], v[124:127]
	v_mfma_f32_16x16x32_bf16 v[128:131], v[88:91], v[64:67], v[128:131]
	v_mfma_f32_16x16x32_bf16 v[132:135], v[76:79], v[68:71], v[132:135]
	v_mfma_f32_16x16x32_bf16 v[136:139], v[80:83], v[68:71], v[136:139]
	v_mfma_f32_16x16x32_bf16 v[140:143], v[84:87], v[68:71], v[140:143]
	v_mfma_f32_16x16x32_bf16 v[144:147], v[88:91], v[68:71], v[144:147]
	v_mfma_f32_16x16x32_bf16 v[148:151], v[76:79], v[72:75], v[148:151]
	v_mfma_f32_16x16x32_bf16 v[152:155], v[80:83], v[72:75], v[152:155]
	v_mfma_f32_16x16x32_bf16 v[156:159], v[84:87], v[72:75], v[156:159]
	v_mfma_f32_16x16x32_bf16 v[160:163], v[88:91], v[72:75], v[160:163]
	global_load_dwordx4 v[60:63], v6, s[10:11] offset:640
	global_load_dwordx4 v[64:67], v7, s[10:11] offset:640
	global_load_dwordx4 v[68:71], v8, s[10:11] offset:640
	global_load_dwordx4 v[72:75], v56, s[10:11] offset:640
	global_load_dwordx4 v[76:79], v6, s[24:25] offset:640
	global_load_dwordx4 v[80:83], v7, s[24:25] offset:640
	global_load_dwordx4 v[84:87], v8, s[24:25] offset:640
	global_load_dwordx4 v[88:91], v56, s[24:25] offset:640
	s_waitcnt vmcnt(24)
	ds_bpermute_b32 v196, v0, v196
	ds_bpermute_b32 v197, v0, v197
	ds_bpermute_b32 v198, v0, v198
	ds_bpermute_b32 v199, v0, v199
	ds_bpermute_b32 v200, v0, v200
	ds_bpermute_b32 v201, v0, v201
	ds_bpermute_b32 v202, v0, v202
	ds_bpermute_b32 v203, v0, v203
	ds_bpermute_b32 v204, v0, v204
	ds_bpermute_b32 v205, v0, v205
	ds_bpermute_b32 v206, v0, v206
	ds_bpermute_b32 v207, v0, v207
	ds_bpermute_b32 v208, v0, v208
	ds_bpermute_b32 v209, v0, v209
	ds_bpermute_b32 v210, v0, v210
	ds_bpermute_b32 v211, v0, v211
	ds_bpermute_b32 v212, v0, v212
	ds_bpermute_b32 v213, v0, v213
	ds_bpermute_b32 v214, v0, v214
	ds_bpermute_b32 v215, v0, v215
	ds_bpermute_b32 v44, v0, v44
	ds_bpermute_b32 v45, v0, v45
	ds_bpermute_b32 v46, v0, v46
	ds_bpermute_b32 v47, v0, v47
	ds_bpermute_b32 v48, v0, v48
	ds_bpermute_b32 v49, v0, v49
	ds_bpermute_b32 v50, v0, v50
	ds_bpermute_b32 v51, v0, v51
	ds_bpermute_b32 v52, v0, v52
	ds_bpermute_b32 v53, v0, v53
	ds_bpermute_b32 v54, v0, v54
	ds_bpermute_b32 v55, v0, v55
	s_waitcnt lgkmcnt(0)
	v_mfma_f32_16x16x32_bf16 v[100:103], v[212:215], v[196:199], v[100:103]
	v_mfma_f32_16x16x32_bf16 v[104:107], v[44:47], v[196:199], v[104:107]
	v_mfma_f32_16x16x32_bf16 v[108:111], v[48:51], v[196:199], v[108:111]
	v_mfma_f32_16x16x32_bf16 v[112:115], v[52:55], v[196:199], v[112:115]
	v_mfma_f32_16x16x32_bf16 v[116:119], v[212:215], v[200:203], v[116:119]
	v_mfma_f32_16x16x32_bf16 v[120:123], v[44:47], v[200:203], v[120:123]
	v_mfma_f32_16x16x32_bf16 v[124:127], v[48:51], v[200:203], v[124:127]
	v_mfma_f32_16x16x32_bf16 v[128:131], v[52:55], v[200:203], v[128:131]
	v_mfma_f32_16x16x32_bf16 v[132:135], v[212:215], v[204:207], v[132:135]
	v_mfma_f32_16x16x32_bf16 v[136:139], v[44:47], v[204:207], v[136:139]
	v_mfma_f32_16x16x32_bf16 v[140:143], v[48:51], v[204:207], v[140:143]
	v_mfma_f32_16x16x32_bf16 v[144:147], v[52:55], v[204:207], v[144:147]
	v_mfma_f32_16x16x32_bf16 v[148:151], v[212:215], v[208:211], v[148:151]
	v_mfma_f32_16x16x32_bf16 v[152:155], v[44:47], v[208:211], v[152:155]
	v_mfma_f32_16x16x32_bf16 v[156:159], v[48:51], v[208:211], v[156:159]
	v_mfma_f32_16x16x32_bf16 v[160:163], v[52:55], v[208:211], v[160:163]
	global_load_dwordx4 v[196:199], v6, s[10:11] offset:704
	global_load_dwordx4 v[200:203], v7, s[10:11] offset:704
	global_load_dwordx4 v[204:207], v8, s[10:11] offset:704
	global_load_dwordx4 v[208:211], v56, s[10:11] offset:704
	global_load_dwordx4 v[212:215], v6, s[24:25] offset:704
	global_load_dwordx4 v[44:47], v7, s[24:25] offset:704
	global_load_dwordx4 v[48:51], v8, s[24:25] offset:704
	global_load_dwordx4 v[52:55], v56, s[24:25] offset:704
	s_waitcnt vmcnt(24)
	ds_bpermute_b32 v164, v0, v164
	ds_bpermute_b32 v165, v0, v165
	ds_bpermute_b32 v166, v0, v166
	ds_bpermute_b32 v167, v0, v167
	ds_bpermute_b32 v168, v0, v168
	ds_bpermute_b32 v169, v0, v169
	ds_bpermute_b32 v170, v0, v170
	ds_bpermute_b32 v171, v0, v171
	ds_bpermute_b32 v172, v0, v172
	ds_bpermute_b32 v173, v0, v173
	ds_bpermute_b32 v174, v0, v174
	ds_bpermute_b32 v175, v0, v175
	ds_bpermute_b32 v176, v0, v176
	ds_bpermute_b32 v177, v0, v177
	ds_bpermute_b32 v178, v0, v178
	ds_bpermute_b32 v179, v0, v179
	ds_bpermute_b32 v180, v0, v180
	ds_bpermute_b32 v181, v0, v181
	ds_bpermute_b32 v182, v0, v182
	ds_bpermute_b32 v183, v0, v183
	ds_bpermute_b32 v184, v0, v184
	ds_bpermute_b32 v185, v0, v185
	ds_bpermute_b32 v186, v0, v186
	ds_bpermute_b32 v187, v0, v187
	ds_bpermute_b32 v188, v0, v188
	ds_bpermute_b32 v189, v0, v189
	ds_bpermute_b32 v190, v0, v190
	ds_bpermute_b32 v191, v0, v191
	ds_bpermute_b32 v192, v0, v192
	ds_bpermute_b32 v193, v0, v193
	ds_bpermute_b32 v194, v0, v194
	ds_bpermute_b32 v195, v0, v195
	s_waitcnt lgkmcnt(0)
	v_mfma_f32_16x16x32_bf16 v[100:103], v[180:183], v[164:167], v[100:103]
	v_mfma_f32_16x16x32_bf16 v[104:107], v[184:187], v[164:167], v[104:107]
	v_mfma_f32_16x16x32_bf16 v[108:111], v[188:191], v[164:167], v[108:111]
	v_mfma_f32_16x16x32_bf16 v[112:115], v[192:195], v[164:167], v[112:115]
	v_mfma_f32_16x16x32_bf16 v[116:119], v[180:183], v[168:171], v[116:119]
	v_mfma_f32_16x16x32_bf16 v[120:123], v[184:187], v[168:171], v[120:123]
	v_mfma_f32_16x16x32_bf16 v[124:127], v[188:191], v[168:171], v[124:127]
	v_mfma_f32_16x16x32_bf16 v[128:131], v[192:195], v[168:171], v[128:131]
	v_mfma_f32_16x16x32_bf16 v[132:135], v[180:183], v[172:175], v[132:135]
	v_mfma_f32_16x16x32_bf16 v[136:139], v[184:187], v[172:175], v[136:139]
	v_mfma_f32_16x16x32_bf16 v[140:143], v[188:191], v[172:175], v[140:143]
	v_mfma_f32_16x16x32_bf16 v[144:147], v[192:195], v[172:175], v[144:147]
	v_mfma_f32_16x16x32_bf16 v[148:151], v[180:183], v[176:179], v[148:151]
	v_mfma_f32_16x16x32_bf16 v[152:155], v[184:187], v[176:179], v[152:155]
	v_mfma_f32_16x16x32_bf16 v[156:159], v[188:191], v[176:179], v[156:159]
	v_mfma_f32_16x16x32_bf16 v[160:163], v[192:195], v[176:179], v[160:163]
	global_load_dwordx4 v[164:167], v6, s[10:11] offset:768
	global_load_dwordx4 v[168:171], v7, s[10:11] offset:768
	global_load_dwordx4 v[172:175], v8, s[10:11] offset:768
	global_load_dwordx4 v[176:179], v56, s[10:11] offset:768
	global_load_dwordx4 v[180:183], v6, s[24:25] offset:768
	global_load_dwordx4 v[184:187], v7, s[24:25] offset:768
	global_load_dwordx4 v[188:191], v8, s[24:25] offset:768
	global_load_dwordx4 v[192:195], v56, s[24:25] offset:768
	s_waitcnt vmcnt(24)
	ds_bpermute_b32 v12, v0, v12
	ds_bpermute_b32 v13, v0, v13
	ds_bpermute_b32 v14, v0, v14
	ds_bpermute_b32 v15, v0, v15
	ds_bpermute_b32 v16, v0, v16
	ds_bpermute_b32 v17, v0, v17
	ds_bpermute_b32 v18, v0, v18
	ds_bpermute_b32 v19, v0, v19
	ds_bpermute_b32 v20, v0, v20
	ds_bpermute_b32 v21, v0, v21
	ds_bpermute_b32 v22, v0, v22
	ds_bpermute_b32 v23, v0, v23
	ds_bpermute_b32 v24, v0, v24
	ds_bpermute_b32 v25, v0, v25
	ds_bpermute_b32 v26, v0, v26
	ds_bpermute_b32 v27, v0, v27
	ds_bpermute_b32 v28, v0, v28
	ds_bpermute_b32 v29, v0, v29
	ds_bpermute_b32 v30, v0, v30
	ds_bpermute_b32 v31, v0, v31
	ds_bpermute_b32 v32, v0, v32
	ds_bpermute_b32 v33, v0, v33
	ds_bpermute_b32 v34, v0, v34
	ds_bpermute_b32 v35, v0, v35
	ds_bpermute_b32 v36, v0, v36
	ds_bpermute_b32 v37, v0, v37
	ds_bpermute_b32 v38, v0, v38
	ds_bpermute_b32 v39, v0, v39
	ds_bpermute_b32 v40, v0, v40
	ds_bpermute_b32 v41, v0, v41
	ds_bpermute_b32 v42, v0, v42
	ds_bpermute_b32 v43, v0, v43
	s_waitcnt lgkmcnt(0)
	v_mfma_f32_16x16x32_bf16 v[100:103], v[28:31], v[12:15], v[100:103]
	v_mfma_f32_16x16x32_bf16 v[104:107], v[32:35], v[12:15], v[104:107]
	v_mfma_f32_16x16x32_bf16 v[108:111], v[36:39], v[12:15], v[108:111]
	v_mfma_f32_16x16x32_bf16 v[112:115], v[40:43], v[12:15], v[112:115]
	v_mfma_f32_16x16x32_bf16 v[116:119], v[28:31], v[16:19], v[116:119]
	v_mfma_f32_16x16x32_bf16 v[120:123], v[32:35], v[16:19], v[120:123]
	v_mfma_f32_16x16x32_bf16 v[124:127], v[36:39], v[16:19], v[124:127]
	v_mfma_f32_16x16x32_bf16 v[128:131], v[40:43], v[16:19], v[128:131]
	v_mfma_f32_16x16x32_bf16 v[132:135], v[28:31], v[20:23], v[132:135]
	v_mfma_f32_16x16x32_bf16 v[136:139], v[32:35], v[20:23], v[136:139]
	v_mfma_f32_16x16x32_bf16 v[140:143], v[36:39], v[20:23], v[140:143]
	v_mfma_f32_16x16x32_bf16 v[144:147], v[40:43], v[20:23], v[144:147]
	v_mfma_f32_16x16x32_bf16 v[148:151], v[28:31], v[24:27], v[148:151]
	v_mfma_f32_16x16x32_bf16 v[152:155], v[32:35], v[24:27], v[152:155]
	v_mfma_f32_16x16x32_bf16 v[156:159], v[36:39], v[24:27], v[156:159]
	v_mfma_f32_16x16x32_bf16 v[160:163], v[40:43], v[24:27], v[160:163]
	global_load_dwordx4 v[12:15], v6, s[10:11] offset:832
	global_load_dwordx4 v[16:19], v7, s[10:11] offset:832
	global_load_dwordx4 v[20:23], v8, s[10:11] offset:832
	global_load_dwordx4 v[24:27], v56, s[10:11] offset:832
	global_load_dwordx4 v[28:31], v6, s[24:25] offset:832
	global_load_dwordx4 v[32:35], v7, s[24:25] offset:832
	global_load_dwordx4 v[36:39], v8, s[24:25] offset:832
	global_load_dwordx4 v[40:43], v56, s[24:25] offset:832
	s_waitcnt vmcnt(24)
	ds_bpermute_b32 v60, v0, v60
	ds_bpermute_b32 v61, v0, v61
	ds_bpermute_b32 v62, v0, v62
	ds_bpermute_b32 v63, v0, v63
	ds_bpermute_b32 v64, v0, v64
	ds_bpermute_b32 v65, v0, v65
	ds_bpermute_b32 v66, v0, v66
	ds_bpermute_b32 v67, v0, v67
	ds_bpermute_b32 v68, v0, v68
	ds_bpermute_b32 v69, v0, v69
	ds_bpermute_b32 v70, v0, v70
	ds_bpermute_b32 v71, v0, v71
	ds_bpermute_b32 v72, v0, v72
	ds_bpermute_b32 v73, v0, v73
	ds_bpermute_b32 v74, v0, v74
	ds_bpermute_b32 v75, v0, v75
	ds_bpermute_b32 v76, v0, v76
	ds_bpermute_b32 v77, v0, v77
	ds_bpermute_b32 v78, v0, v78
	ds_bpermute_b32 v79, v0, v79
	ds_bpermute_b32 v80, v0, v80
	ds_bpermute_b32 v81, v0, v81
	ds_bpermute_b32 v82, v0, v82
	ds_bpermute_b32 v83, v0, v83
	ds_bpermute_b32 v84, v0, v84
	ds_bpermute_b32 v85, v0, v85
	ds_bpermute_b32 v86, v0, v86
	ds_bpermute_b32 v87, v0, v87
	ds_bpermute_b32 v88, v0, v88
	ds_bpermute_b32 v89, v0, v89
	ds_bpermute_b32 v90, v0, v90
	ds_bpermute_b32 v91, v0, v91
	s_waitcnt lgkmcnt(0)
	v_mfma_f32_16x16x32_bf16 v[100:103], v[76:79], v[60:63], v[100:103]
	v_mfma_f32_16x16x32_bf16 v[104:107], v[80:83], v[60:63], v[104:107]
	v_mfma_f32_16x16x32_bf16 v[108:111], v[84:87], v[60:63], v[108:111]
	v_mfma_f32_16x16x32_bf16 v[112:115], v[88:91], v[60:63], v[112:115]
	v_mfma_f32_16x16x32_bf16 v[116:119], v[76:79], v[64:67], v[116:119]
	v_mfma_f32_16x16x32_bf16 v[120:123], v[80:83], v[64:67], v[120:123]
	v_mfma_f32_16x16x32_bf16 v[124:127], v[84:87], v[64:67], v[124:127]
	v_mfma_f32_16x16x32_bf16 v[128:131], v[88:91], v[64:67], v[128:131]
	v_mfma_f32_16x16x32_bf16 v[132:135], v[76:79], v[68:71], v[132:135]
	v_mfma_f32_16x16x32_bf16 v[136:139], v[80:83], v[68:71], v[136:139]
	v_mfma_f32_16x16x32_bf16 v[140:143], v[84:87], v[68:71], v[140:143]
	v_mfma_f32_16x16x32_bf16 v[144:147], v[88:91], v[68:71], v[144:147]
	v_mfma_f32_16x16x32_bf16 v[148:151], v[76:79], v[72:75], v[148:151]
	v_mfma_f32_16x16x32_bf16 v[152:155], v[80:83], v[72:75], v[152:155]
	v_mfma_f32_16x16x32_bf16 v[156:159], v[84:87], v[72:75], v[156:159]
	v_mfma_f32_16x16x32_bf16 v[160:163], v[88:91], v[72:75], v[160:163]
	global_load_dwordx4 v[60:63], v6, s[10:11] offset:896
	global_load_dwordx4 v[64:67], v7, s[10:11] offset:896
	global_load_dwordx4 v[68:71], v8, s[10:11] offset:896
	global_load_dwordx4 v[72:75], v56, s[10:11] offset:896
	global_load_dwordx4 v[76:79], v6, s[24:25] offset:896
	global_load_dwordx4 v[80:83], v7, s[24:25] offset:896
	global_load_dwordx4 v[84:87], v8, s[24:25] offset:896
	global_load_dwordx4 v[88:91], v56, s[24:25] offset:896
	s_waitcnt vmcnt(24)
	ds_bpermute_b32 v196, v0, v196
	ds_bpermute_b32 v197, v0, v197
	ds_bpermute_b32 v198, v0, v198
	ds_bpermute_b32 v199, v0, v199
	ds_bpermute_b32 v200, v0, v200
	ds_bpermute_b32 v201, v0, v201
	ds_bpermute_b32 v202, v0, v202
	ds_bpermute_b32 v203, v0, v203
	ds_bpermute_b32 v204, v0, v204
	ds_bpermute_b32 v205, v0, v205
	ds_bpermute_b32 v206, v0, v206
	ds_bpermute_b32 v207, v0, v207
	ds_bpermute_b32 v208, v0, v208
	ds_bpermute_b32 v209, v0, v209
	ds_bpermute_b32 v210, v0, v210
	ds_bpermute_b32 v211, v0, v211
	ds_bpermute_b32 v212, v0, v212
	ds_bpermute_b32 v213, v0, v213
	ds_bpermute_b32 v214, v0, v214
	ds_bpermute_b32 v215, v0, v215
	ds_bpermute_b32 v44, v0, v44
	ds_bpermute_b32 v45, v0, v45
	ds_bpermute_b32 v46, v0, v46
	ds_bpermute_b32 v47, v0, v47
	ds_bpermute_b32 v48, v0, v48
	ds_bpermute_b32 v49, v0, v49
	ds_bpermute_b32 v50, v0, v50
	ds_bpermute_b32 v51, v0, v51
	ds_bpermute_b32 v52, v0, v52
	ds_bpermute_b32 v53, v0, v53
	ds_bpermute_b32 v54, v0, v54
	ds_bpermute_b32 v55, v0, v55
	s_waitcnt lgkmcnt(0)
	v_mfma_f32_16x16x32_bf16 v[100:103], v[212:215], v[196:199], v[100:103]
	v_mfma_f32_16x16x32_bf16 v[104:107], v[44:47], v[196:199], v[104:107]
	v_mfma_f32_16x16x32_bf16 v[108:111], v[48:51], v[196:199], v[108:111]
	v_mfma_f32_16x16x32_bf16 v[112:115], v[52:55], v[196:199], v[112:115]
	v_mfma_f32_16x16x32_bf16 v[116:119], v[212:215], v[200:203], v[116:119]
	v_mfma_f32_16x16x32_bf16 v[120:123], v[44:47], v[200:203], v[120:123]
	v_mfma_f32_16x16x32_bf16 v[124:127], v[48:51], v[200:203], v[124:127]
	v_mfma_f32_16x16x32_bf16 v[128:131], v[52:55], v[200:203], v[128:131]
	v_mfma_f32_16x16x32_bf16 v[132:135], v[212:215], v[204:207], v[132:135]
	v_mfma_f32_16x16x32_bf16 v[136:139], v[44:47], v[204:207], v[136:139]
	v_mfma_f32_16x16x32_bf16 v[140:143], v[48:51], v[204:207], v[140:143]
	v_mfma_f32_16x16x32_bf16 v[144:147], v[52:55], v[204:207], v[144:147]
	v_mfma_f32_16x16x32_bf16 v[148:151], v[212:215], v[208:211], v[148:151]
	v_mfma_f32_16x16x32_bf16 v[152:155], v[44:47], v[208:211], v[152:155]
	v_mfma_f32_16x16x32_bf16 v[156:159], v[48:51], v[208:211], v[156:159]
	v_mfma_f32_16x16x32_bf16 v[160:163], v[52:55], v[208:211], v[160:163]
	global_load_dwordx4 v[196:199], v6, s[10:11] offset:960
	global_load_dwordx4 v[200:203], v7, s[10:11] offset:960
	global_load_dwordx4 v[204:207], v8, s[10:11] offset:960
	global_load_dwordx4 v[208:211], v56, s[10:11] offset:960
	global_load_dwordx4 v[212:215], v6, s[24:25] offset:960
	global_load_dwordx4 v[44:47], v7, s[24:25] offset:960
	global_load_dwordx4 v[48:51], v8, s[24:25] offset:960
	global_load_dwordx4 v[52:55], v56, s[24:25] offset:960
	s_waitcnt vmcnt(24)
	ds_bpermute_b32 v164, v0, v164
	ds_bpermute_b32 v165, v0, v165
	ds_bpermute_b32 v166, v0, v166
	ds_bpermute_b32 v167, v0, v167
	ds_bpermute_b32 v168, v0, v168
	ds_bpermute_b32 v169, v0, v169
	ds_bpermute_b32 v170, v0, v170
	ds_bpermute_b32 v171, v0, v171
	ds_bpermute_b32 v172, v0, v172
	ds_bpermute_b32 v173, v0, v173
	ds_bpermute_b32 v174, v0, v174
	ds_bpermute_b32 v175, v0, v175
	ds_bpermute_b32 v176, v0, v176
	ds_bpermute_b32 v177, v0, v177
	ds_bpermute_b32 v178, v0, v178
	ds_bpermute_b32 v179, v0, v179
	ds_bpermute_b32 v180, v0, v180
	ds_bpermute_b32 v181, v0, v181
	ds_bpermute_b32 v182, v0, v182
	ds_bpermute_b32 v183, v0, v183
	ds_bpermute_b32 v184, v0, v184
	ds_bpermute_b32 v185, v0, v185
	ds_bpermute_b32 v186, v0, v186
	ds_bpermute_b32 v187, v0, v187
	ds_bpermute_b32 v188, v0, v188
	ds_bpermute_b32 v189, v0, v189
	ds_bpermute_b32 v190, v0, v190
	ds_bpermute_b32 v191, v0, v191
	ds_bpermute_b32 v192, v0, v192
	ds_bpermute_b32 v193, v0, v193
	ds_bpermute_b32 v194, v0, v194
	ds_bpermute_b32 v195, v0, v195
	s_waitcnt lgkmcnt(0)
	v_mfma_f32_16x16x32_bf16 v[100:103], v[180:183], v[164:167], v[100:103]
	v_mfma_f32_16x16x32_bf16 v[104:107], v[184:187], v[164:167], v[104:107]
	v_mfma_f32_16x16x32_bf16 v[108:111], v[188:191], v[164:167], v[108:111]
	v_mfma_f32_16x16x32_bf16 v[112:115], v[192:195], v[164:167], v[112:115]
	v_mfma_f32_16x16x32_bf16 v[116:119], v[180:183], v[168:171], v[116:119]
	v_mfma_f32_16x16x32_bf16 v[120:123], v[184:187], v[168:171], v[120:123]
	v_mfma_f32_16x16x32_bf16 v[124:127], v[188:191], v[168:171], v[124:127]
	v_mfma_f32_16x16x32_bf16 v[128:131], v[192:195], v[168:171], v[128:131]
	v_mfma_f32_16x16x32_bf16 v[132:135], v[180:183], v[172:175], v[132:135]
	v_mfma_f32_16x16x32_bf16 v[136:139], v[184:187], v[172:175], v[136:139]
	v_mfma_f32_16x16x32_bf16 v[140:143], v[188:191], v[172:175], v[140:143]
	v_mfma_f32_16x16x32_bf16 v[144:147], v[192:195], v[172:175], v[144:147]
	v_mfma_f32_16x16x32_bf16 v[148:151], v[180:183], v[176:179], v[148:151]
	v_mfma_f32_16x16x32_bf16 v[152:155], v[184:187], v[176:179], v[152:155]
	v_mfma_f32_16x16x32_bf16 v[156:159], v[188:191], v[176:179], v[156:159]
	v_mfma_f32_16x16x32_bf16 v[160:163], v[192:195], v[176:179], v[160:163]
	s_waitcnt vmcnt(16)
	ds_bpermute_b32 v12, v0, v12
	ds_bpermute_b32 v13, v0, v13
	ds_bpermute_b32 v14, v0, v14
	ds_bpermute_b32 v15, v0, v15
	ds_bpermute_b32 v16, v0, v16
	ds_bpermute_b32 v17, v0, v17
	ds_bpermute_b32 v18, v0, v18
	ds_bpermute_b32 v19, v0, v19
	ds_bpermute_b32 v20, v0, v20
	ds_bpermute_b32 v21, v0, v21
	ds_bpermute_b32 v22, v0, v22
	ds_bpermute_b32 v23, v0, v23
	ds_bpermute_b32 v24, v0, v24
	ds_bpermute_b32 v25, v0, v25
	ds_bpermute_b32 v26, v0, v26
	ds_bpermute_b32 v27, v0, v27
	ds_bpermute_b32 v28, v0, v28
	ds_bpermute_b32 v29, v0, v29
	ds_bpermute_b32 v30, v0, v30
	ds_bpermute_b32 v31, v0, v31
	ds_bpermute_b32 v32, v0, v32
	ds_bpermute_b32 v33, v0, v33
	ds_bpermute_b32 v34, v0, v34
	ds_bpermute_b32 v35, v0, v35
	ds_bpermute_b32 v36, v0, v36
	ds_bpermute_b32 v37, v0, v37
	ds_bpermute_b32 v38, v0, v38
	ds_bpermute_b32 v39, v0, v39
	ds_bpermute_b32 v40, v0, v40
	ds_bpermute_b32 v41, v0, v41
	ds_bpermute_b32 v42, v0, v42
	ds_bpermute_b32 v43, v0, v43
	s_waitcnt lgkmcnt(0)
	v_mfma_f32_16x16x32_bf16 v[100:103], v[28:31], v[12:15], v[100:103]
	v_mfma_f32_16x16x32_bf16 v[104:107], v[32:35], v[12:15], v[104:107]
	v_mfma_f32_16x16x32_bf16 v[108:111], v[36:39], v[12:15], v[108:111]
	v_mfma_f32_16x16x32_bf16 v[112:115], v[40:43], v[12:15], v[112:115]
	v_mfma_f32_16x16x32_bf16 v[116:119], v[28:31], v[16:19], v[116:119]
	v_mfma_f32_16x16x32_bf16 v[120:123], v[32:35], v[16:19], v[120:123]
	v_mfma_f32_16x16x32_bf16 v[124:127], v[36:39], v[16:19], v[124:127]
	v_mfma_f32_16x16x32_bf16 v[128:131], v[40:43], v[16:19], v[128:131]
	v_mfma_f32_16x16x32_bf16 v[132:135], v[28:31], v[20:23], v[132:135]
	v_mfma_f32_16x16x32_bf16 v[136:139], v[32:35], v[20:23], v[136:139]
	v_mfma_f32_16x16x32_bf16 v[140:143], v[36:39], v[20:23], v[140:143]
	v_mfma_f32_16x16x32_bf16 v[144:147], v[40:43], v[20:23], v[144:147]
	v_mfma_f32_16x16x32_bf16 v[148:151], v[28:31], v[24:27], v[148:151]
	v_mfma_f32_16x16x32_bf16 v[152:155], v[32:35], v[24:27], v[152:155]
	v_mfma_f32_16x16x32_bf16 v[156:159], v[36:39], v[24:27], v[156:159]
	v_mfma_f32_16x16x32_bf16 v[160:163], v[40:43], v[24:27], v[160:163]
	s_waitcnt vmcnt(8)
	ds_bpermute_b32 v60, v0, v60
	ds_bpermute_b32 v61, v0, v61
	ds_bpermute_b32 v62, v0, v62
	ds_bpermute_b32 v63, v0, v63
	ds_bpermute_b32 v64, v0, v64
	ds_bpermute_b32 v65, v0, v65
	ds_bpermute_b32 v66, v0, v66
	ds_bpermute_b32 v67, v0, v67
	ds_bpermute_b32 v68, v0, v68
	ds_bpermute_b32 v69, v0, v69
	ds_bpermute_b32 v70, v0, v70
	ds_bpermute_b32 v71, v0, v71
	ds_bpermute_b32 v72, v0, v72
	ds_bpermute_b32 v73, v0, v73
	ds_bpermute_b32 v74, v0, v74
	ds_bpermute_b32 v75, v0, v75
	ds_bpermute_b32 v76, v0, v76
	ds_bpermute_b32 v77, v0, v77
	ds_bpermute_b32 v78, v0, v78
	ds_bpermute_b32 v79, v0, v79
	ds_bpermute_b32 v80, v0, v80
	ds_bpermute_b32 v81, v0, v81
	ds_bpermute_b32 v82, v0, v82
	ds_bpermute_b32 v83, v0, v83
	ds_bpermute_b32 v84, v0, v84
	ds_bpermute_b32 v85, v0, v85
	ds_bpermute_b32 v86, v0, v86
	ds_bpermute_b32 v87, v0, v87
	ds_bpermute_b32 v88, v0, v88
	ds_bpermute_b32 v89, v0, v89
	ds_bpermute_b32 v90, v0, v90
	ds_bpermute_b32 v91, v0, v91
	s_waitcnt lgkmcnt(0)
	v_mfma_f32_16x16x32_bf16 v[100:103], v[76:79], v[60:63], v[100:103]
	v_mfma_f32_16x16x32_bf16 v[104:107], v[80:83], v[60:63], v[104:107]
	v_mfma_f32_16x16x32_bf16 v[108:111], v[84:87], v[60:63], v[108:111]
	v_mfma_f32_16x16x32_bf16 v[112:115], v[88:91], v[60:63], v[112:115]
	v_mfma_f32_16x16x32_bf16 v[116:119], v[76:79], v[64:67], v[116:119]
	v_mfma_f32_16x16x32_bf16 v[120:123], v[80:83], v[64:67], v[120:123]
	v_mfma_f32_16x16x32_bf16 v[124:127], v[84:87], v[64:67], v[124:127]
	v_mfma_f32_16x16x32_bf16 v[128:131], v[88:91], v[64:67], v[128:131]
	v_mfma_f32_16x16x32_bf16 v[132:135], v[76:79], v[68:71], v[132:135]
	v_mfma_f32_16x16x32_bf16 v[136:139], v[80:83], v[68:71], v[136:139]
	v_mfma_f32_16x16x32_bf16 v[140:143], v[84:87], v[68:71], v[140:143]
	v_mfma_f32_16x16x32_bf16 v[144:147], v[88:91], v[68:71], v[144:147]
	v_mfma_f32_16x16x32_bf16 v[148:151], v[76:79], v[72:75], v[148:151]
	v_mfma_f32_16x16x32_bf16 v[152:155], v[80:83], v[72:75], v[152:155]
	v_mfma_f32_16x16x32_bf16 v[156:159], v[84:87], v[72:75], v[156:159]
	v_mfma_f32_16x16x32_bf16 v[160:163], v[88:91], v[72:75], v[160:163]
	s_waitcnt vmcnt(0)
	ds_bpermute_b32 v196, v0, v196
	ds_bpermute_b32 v197, v0, v197
	ds_bpermute_b32 v198, v0, v198
	ds_bpermute_b32 v199, v0, v199
	ds_bpermute_b32 v200, v0, v200
	ds_bpermute_b32 v201, v0, v201
	ds_bpermute_b32 v202, v0, v202
	ds_bpermute_b32 v203, v0, v203
	ds_bpermute_b32 v204, v0, v204
	ds_bpermute_b32 v205, v0, v205
	ds_bpermute_b32 v206, v0, v206
	ds_bpermute_b32 v207, v0, v207
	ds_bpermute_b32 v208, v0, v208
	ds_bpermute_b32 v209, v0, v209
	ds_bpermute_b32 v210, v0, v210
	ds_bpermute_b32 v211, v0, v211
	ds_bpermute_b32 v212, v0, v212
	ds_bpermute_b32 v213, v0, v213
	ds_bpermute_b32 v214, v0, v214
	ds_bpermute_b32 v215, v0, v215
	ds_bpermute_b32 v44, v0, v44
	ds_bpermute_b32 v45, v0, v45
	ds_bpermute_b32 v46, v0, v46
	ds_bpermute_b32 v47, v0, v47
	ds_bpermute_b32 v48, v0, v48
	ds_bpermute_b32 v49, v0, v49
	ds_bpermute_b32 v50, v0, v50
	ds_bpermute_b32 v51, v0, v51
	ds_bpermute_b32 v52, v0, v52
	ds_bpermute_b32 v53, v0, v53
	ds_bpermute_b32 v54, v0, v54
	ds_bpermute_b32 v55, v0, v55
	s_waitcnt lgkmcnt(0)
	v_mfma_f32_16x16x32_bf16 v[100:103], v[212:215], v[196:199], v[100:103]
	v_mfma_f32_16x16x32_bf16 v[104:107], v[44:47], v[196:199], v[104:107]
	v_mfma_f32_16x16x32_bf16 v[108:111], v[48:51], v[196:199], v[108:111]
	v_mfma_f32_16x16x32_bf16 v[112:115], v[52:55], v[196:199], v[112:115]
	v_mfma_f32_16x16x32_bf16 v[116:119], v[212:215], v[200:203], v[116:119]
	v_mfma_f32_16x16x32_bf16 v[120:123], v[44:47], v[200:203], v[120:123]
	v_mfma_f32_16x16x32_bf16 v[124:127], v[48:51], v[200:203], v[124:127]
	v_mfma_f32_16x16x32_bf16 v[128:131], v[52:55], v[200:203], v[128:131]
	v_mfma_f32_16x16x32_bf16 v[132:135], v[212:215], v[204:207], v[132:135]
	v_mfma_f32_16x16x32_bf16 v[136:139], v[44:47], v[204:207], v[136:139]
	v_mfma_f32_16x16x32_bf16 v[140:143], v[48:51], v[204:207], v[140:143]
	v_mfma_f32_16x16x32_bf16 v[144:147], v[52:55], v[204:207], v[144:147]
	v_mfma_f32_16x16x32_bf16 v[148:151], v[212:215], v[208:211], v[148:151]
	v_mfma_f32_16x16x32_bf16 v[152:155], v[44:47], v[208:211], v[152:155]
	v_mfma_f32_16x16x32_bf16 v[156:159], v[48:51], v[208:211], v[156:159]
	v_mfma_f32_16x16x32_bf16 v[160:163], v[52:55], v[208:211], v[160:163]
	ds_write_b128 v57, v[100:103] offset:0
	ds_write_b128 v1, v[104:107] offset:0
	ds_write_b128 v234, v[108:111] offset:0
	ds_write_b128 v235, v[112:115] offset:0
	ds_write_b128 v57, v[116:119] offset:4096
	ds_write_b128 v1, v[120:123] offset:4096
	ds_write_b128 v234, v[124:127] offset:4096
	ds_write_b128 v235, v[128:131] offset:4096
	ds_write_b128 v57, v[132:135] offset:8192
	ds_write_b128 v1, v[136:139] offset:8192
	ds_write_b128 v234, v[140:143] offset:8192
	ds_write_b128 v235, v[144:147] offset:8192
	ds_write_b128 v57, v[148:151] offset:12288
	ds_write_b128 v1, v[152:155] offset:12288
	ds_write_b128 v234, v[156:159] offset:12288
	ds_write_b128 v235, v[160:163] offset:12288
	s_waitcnt lgkmcnt(0)
	s_barrier
	ds_read_b128 v[100:103], v59 offset:0
	ds_read_b128 v[104:107], v248 offset:0
	ds_read_b128 v[108:111], v59 offset:16384
	ds_read_b128 v[112:115], v248 offset:16384
	ds_read_b128 v[116:119], v59 offset:32768
	ds_read_b128 v[120:123], v248 offset:32768
	ds_read_b128 v[124:127], v59 offset:49152
	ds_read_b128 v[128:131], v248 offset:49152
	ds_read_b128 v[132:135], v98 offset:0
	ds_read_b128 v[136:139], v249 offset:0
	ds_read_b128 v[140:143], v98 offset:16384
	ds_read_b128 v[144:147], v249 offset:16384
	ds_read_b128 v[148:151], v98 offset:32768
	ds_read_b128 v[152:155], v249 offset:32768
	ds_read_b128 v[156:159], v98 offset:49152
	ds_read_b128 v[160:163], v249 offset:49152
	s_waitcnt lgkmcnt(0)
	s_barrier
	v_pk_add_f32 v[244:245], v[100:101], v[108:109]
	v_pk_add_f32 v[246:247], v[102:103], v[110:111]
	v_pk_add_f32 v[244:245], v[244:245], v[116:117]
	v_pk_add_f32 v[246:247], v[246:247], v[118:119]
	v_pk_add_f32 v[244:245], v[244:245], v[124:125]
	v_pk_add_f32 v[246:247], v[246:247], v[126:127]
	v_pk_add_f32 v[244:245], v[244:245], v[132:133]
	v_pk_add_f32 v[246:247], v[246:247], v[134:135]
	v_pk_add_f32 v[244:245], v[244:245], v[140:141]
	v_pk_add_f32 v[246:247], v[246:247], v[142:143]
	v_pk_add_f32 v[244:245], v[244:245], v[148:149]
	v_pk_add_f32 v[246:247], v[246:247], v[150:151]
	v_pk_add_f32 v[244:245], v[244:245], v[156:157]
	v_pk_add_f32 v[246:247], v[246:247], v[158:159]
	v_pk_add_f32 v[224:225], v[104:105], v[112:113]
	v_pk_add_f32 v[226:227], v[106:107], v[114:115]
	v_pk_add_f32 v[224:225], v[224:225], v[120:121]
	v_pk_add_f32 v[226:227], v[226:227], v[122:123]
	v_pk_add_f32 v[224:225], v[224:225], v[128:129]
	v_pk_add_f32 v[226:227], v[226:227], v[130:131]
	v_pk_add_f32 v[224:225], v[224:225], v[136:137]
	v_pk_add_f32 v[226:227], v[226:227], v[138:139]
	v_pk_add_f32 v[224:225], v[224:225], v[144:145]
	v_pk_add_f32 v[226:227], v[226:227], v[146:147]
	v_pk_add_f32 v[224:225], v[224:225], v[152:153]
	v_pk_add_f32 v[226:227], v[226:227], v[154:155]
	v_pk_add_f32 v[224:225], v[224:225], v[160:161]
	v_pk_add_f32 v[226:227], v[226:227], v[162:163]
	s_lshl_b32 s50, s7, 6
	s_sub_u32 s50, 0x110, s50
	v_cmp_gt_u32_e64 s[46:47], s50, v218
	s_and_saveexec_b64 s[48:49], s[46:47]
	s_cbranch_execz .Lsk_p7_done
	s_waitcnt vmcnt(0)
	v_lshlrev_b32_e32 v164, 16, v220
	v_and_b32_e32 v165, 0xffff0000, v220
	v_lshlrev_b32_e32 v166, 16, v221
	v_and_b32_e32 v167, 0xffff0000, v221
	v_lshlrev_b32_e32 v168, 16, v222
	v_and_b32_e32 v169, 0xffff0000, v222
	v_lshlrev_b32_e32 v170, 16, v223
	v_and_b32_e32 v171, 0xffff0000, v223
	v_add_f32_e32 v164, v164, v244
	v_add_f32_e32 v165, v165, v245
	v_add_f32_e32 v166, v166, v246
	v_add_f32_e32 v167, v167, v247
	v_add_f32_e32 v168, v168, v224
	v_add_f32_e32 v169, v169, v225
	v_add_f32_e32 v170, v170, v226
	v_add_f32_e32 v171, v171, v227
	v_cvt_pk_bf16_f32 v188, v164, v165
	v_cvt_pk_bf16_f32 v189, v166, v167
	v_cvt_pk_bf16_f32 v190, v168, v169
	v_cvt_pk_bf16_f32 v191, v170, v171
	s_nop 0
	global_store_dwordx4 v99, v[188:191], s[42:43]
	v_mul_f32_e32 v176, v164, v164
	v_mul_f32_e32 v177, v166, v166
	v_fmac_f32_e32 v176, v165, v165
	v_fmac_f32_e32 v177, v167, v167
	v_add_f32_e32 v176, v176, v177
	v_mul_f32_e32 v177, v168, v168
	v_mul_f32_e32 v178, v170, v170
	v_fmac_f32_e32 v177, v169, v169
	v_fmac_f32_e32 v178, v171, v171
	v_add_f32_e32 v177, v177, v178
	v_add_f32_e32 v176, v176, v177
	s_nop 1
	v_add_f32_dpp v176, v176, v176 quad_perm:[1,0,3,2] row_mask:0xf bank_mask:0xf bound_ctrl:1
	s_nop 1
	v_add_f32_dpp v176, v176, v176 quad_perm:[2,3,0,1] row_mask:0xf bank_mask:0xf bound_ctrl:1
	s_nop 1
	v_add_f32_dpp v176, v176, v176 row_shr:4 row_mask:0xf bank_mask:0xf bound_ctrl:1
	v_cmp_eq_u32_e64 s[46:47], 7, v228
	s_and_b64 exec, exec, s[46:47]
	global_store_dword v231, v176, s[44:45]
